# scan loops: counted vmcnt instead of vmcnt(0) at loop heads; GEMM K-loops: peeled first iteration with C=0 replaces 128 v_mov zero-init (stacked on v4)
# baseline (speedup 1.0000x reference)
; #define PG8_STAGE(bufoff, gbase, voff) do { _Pragma("unroll") for (int _i = 0; _i < 2; ++_i) \
;         __builtin_amdgcn_global_load_lds((const unsigned*)((const char*)(gbase) + (voff)[_i]), (LAS unsigned*)(lds + (bufoff) + ldsw + _i * 8192), 16, 0, 0); } while (0)
; #define PG8_LDA(dst, b, h) do { _Pragma("unroll") for (int m = 0; m < 4; ++m) _Pragma("unroll") for (int k = 0; k < 2; ++k) dst[m][k] = *(const LAS bf16x8*)(lds + PG8_SA(b, h) + aoff + m * 2048 + k * 1024); } while (0)
; #define PG8_LDB(dst, b, h) do { _Pragma("unroll") for (int n = 0; n < 2; ++n) _Pragma("unroll") for (int k = 0; k < 2; ++k) dst[n][k] = *(const LAS bf16x8*)(lds + PG8_SB(b, h) + boff + n * 2048 + k * 1024); } while (0)
; #define PG8_MMA(ai, bj, At, Bt) do { __builtin_amdgcn_s_setprio(1); _Pragma("unroll") for (int m = 0; m < 4; ++m) _Pragma("unroll") for (int n = 0; n < 2; ++n) _Pragma("unroll") for (int k = 0; k < 2; ++k) \
;         acc[ai][bj][m][n] = __builtin_amdgcn_mfma_f32_16x16x32_bf16(Bt[n][k], At[m][k], acc[ai][bj][m][n], 0, 0, 0); __builtin_amdgcn_s_setprio(0); } while (0)
; #define PG8_WAIT_L(n) asm volatile("s_waitcnt lgkmcnt(" #n ")" ::: "memory")
; #define PG8_BAR __builtin_amdgcn_s_barrier()
; #define PG8_SCHED __builtin_amdgcn_sched_barrier(0)
; template <class Epi>
; DI void gemm_phase(int wv, LAS unsigned char* lds, const GemmD g, const Epi& E) {
;     ...
;         for (int t = 0; t < nt; t += 2) {
;             const bool last = (t == nt - 2);
;             const char* a1 = cA + (size_t)(t + 1) * kstep;
;             const char* a2 = last ? nA : cA + (size_t)(t + 2) * kstep; const char* b2 = last ? nB : cB + (size_t)(t + 2) * kstep;
;             const char* a3 = a2 + kstep; const char* b3 = b2 + kstep;
;             PG8_LDB(B0, 0, 0); PG8_SCHED; PG8_LDA(At, 0, 0); PG8_STAGE(PG8_SA(1, 1), a1 + hstepA, voffA);
;             PG8_WAIT_L(8); PG8_BAR; PG8_WAIT_L(0); PG8_MMA(0, 0, At, B0); PG8_BAR; PG8_SCHED;
;             PG8_LDB(B1, 0, 1); PG8_STAGE(PG8_SB(0, 0), b2, voffB);
;             PG8_BAR; PG8_WAIT_L(0); PG8_MMA(0, 1, At, B1); PG8_BAR;
;             PG8_LDA(At, 0, 1); PG8_STAGE(PG8_SA(0, 0), a2, voffA);
;             PG8_BAR; PG8_WAIT_L(0); PG8_MMA(1, 0, At, B0); PG8_BAR; PG8_SCHED;
.LBB0_98:
	s_ashr_i32 s17, s16, 31
	s_lshl_b64 s[20:21], s[16:17], 19
	s_add_u32 s20, s6, s20
	s_addc_u32 s21, s7, s21
	s_and_b64 s[4:5], s[4:5], exec
	s_cselect_b32 s17, s21, s25
	s_cselect_b32 vcc_lo, s20, s24
	s_add_u32 s4, s24, 0x40080
	s_addc_u32 s5, s25, 0
	s_add_u32 vcc_hi, s22, 0x100
	s_addc_u32 s75, s23, 0
	s_mov_b32 s95, -2
	s_add_u32 s22, s4, 0xfffc0080
	s_addc_u32 s23, s5, -1
	s_add_i32 s3, 0, 0x10000
	v_add_u32_e32 v156, s3, v141
	ds_read_b128 v[144:147], v156
	ds_read_b128 v[148:151], v156 offset:1024
	ds_read_b128 v[152:155], v156 offset:2048
	ds_read_b128 v[156:159], v156 offset:3072
	s_cmp_eq_u32 s95, 12
	s_cselect_b32 s23, s17, s23
	s_cselect_b32 s22, vcc_lo, s22
	s_cselect_b32 s25, s19, s75
	s_cselect_b32 s24, s18, vcc_hi
	v_lshl_add_u64 v[164:165], s[4:5], 0, v[136:137]
	s_add_i32 m0, s15, 0xc000
	ds_read_b128 v[160:163], v143
	ds_read_b128 v[176:179], v143 offset:1024
	ds_read_b128 v[180:183], v143 offset:2048
	ds_read_b128 v[184:187], v143 offset:3072
	ds_read_b128 v[188:191], v143 offset:4096
	ds_read_b128 v[192:195], v143 offset:5120
	ds_read_b128 v[196:199], v143 offset:6144
	ds_read_b128 v[200:203], v143 offset:7168
	global_load_lds_dwordx4 v[164:165], off
	v_lshl_add_u64 v[164:165], s[4:5], 0, v[138:139]
	s_add_i32 m0, s15, 0xe000
	s_nop 0
	global_load_lds_dwordx4 v[164:165], off
	s_waitcnt lgkmcnt(8)
	s_barrier
	s_waitcnt lgkmcnt(0)
	s_setprio 1
	s_waitcnt lgkmcnt(0)
	v_mfma_f32_16x16x32_bf16 v[126:129], v[144:147], v[160:163], 0
	v_mfma_f32_16x16x32_bf16 v[122:125], v[152:155], v[160:163], 0
	v_mfma_f32_16x16x32_bf16 v[118:121], v[144:147], v[180:183], 0
	v_mfma_f32_16x16x32_bf16 v[114:117], v[152:155], v[180:183], 0
	v_mfma_f32_16x16x32_bf16 v[102:105], v[144:147], v[188:191], 0
	v_mfma_f32_16x16x32_bf16 v[98:101], v[152:155], v[188:191], 0
	v_mfma_f32_16x16x32_bf16 v[86:89], v[144:147], v[196:199], 0
	v_mfma_f32_16x16x32_bf16 v[82:85], v[152:155], v[196:199], 0
	v_mfma_f32_16x16x32_bf16 v[126:129], v[148:151], v[176:179], v[126:129]
	v_mfma_f32_16x16x32_bf16 v[122:125], v[156:159], v[176:179], v[122:125]
	v_mfma_f32_16x16x32_bf16 v[118:121], v[148:151], v[184:187], v[118:121]
	v_mfma_f32_16x16x32_bf16 v[114:117], v[156:159], v[184:187], v[114:117]
	v_mfma_f32_16x16x32_bf16 v[102:105], v[148:151], v[192:195], v[102:105]
	v_mfma_f32_16x16x32_bf16 v[98:101], v[156:159], v[192:195], v[98:101]
	v_mfma_f32_16x16x32_bf16 v[86:89], v[148:151], v[200:203], v[86:89]
	v_mfma_f32_16x16x32_bf16 v[82:85], v[156:159], v[200:203], v[82:85]
	s_setprio 0
	s_barrier
	s_add_i32 s2, 0, 0x14000
	v_add_u32_e32 v164, s2, v141
	s_add_i32 s3, s3, s37
	ds_read_b128 v[204:207], v164
	ds_read_b128 v[208:211], v164 offset:1024
	ds_read_b128 v[212:215], v164 offset:2048
	ds_read_b128 v[216:219], v164 offset:3072
	v_lshl_add_u64 v[164:165], s[24:25], 0, v[0:1]
	s_mov_b32 m0, s3
	v_lshl_add_u64 v[168:169], s[24:25], 0, v[130:131]
	global_load_lds_dwordx4 v[164:165], off
	s_add_i32 m0, s3, 0x2000
	s_nop 0
	global_load_lds_dwordx4 v[168:169], off
	s_barrier
	s_waitcnt lgkmcnt(0)
	s_setprio 1
	s_waitcnt lgkmcnt(0)
	v_mfma_f32_16x16x32_bf16 v[110:113], v[204:207], v[160:163], 0
	v_mfma_f32_16x16x32_bf16 v[106:109], v[212:215], v[160:163], 0
	v_mfma_f32_16x16x32_bf16 v[94:97], v[204:207], v[180:183], 0
	v_mfma_f32_16x16x32_bf16 v[90:93], v[212:215], v[180:183], 0
	v_mfma_f32_16x16x32_bf16 v[78:81], v[204:207], v[188:191], 0
	v_mfma_f32_16x16x32_bf16 v[74:77], v[212:215], v[188:191], 0
	v_mfma_f32_16x16x32_bf16 v[70:73], v[204:207], v[196:199], 0
	v_mfma_f32_16x16x32_bf16 v[66:69], v[212:215], v[196:199], 0
	v_mfma_f32_16x16x32_bf16 v[110:113], v[208:211], v[176:179], v[110:113]
	v_mfma_f32_16x16x32_bf16 v[106:109], v[216:219], v[176:179], v[106:109]
	v_mfma_f32_16x16x32_bf16 v[94:97], v[208:211], v[184:187], v[94:97]
	v_mfma_f32_16x16x32_bf16 v[90:93], v[216:219], v[184:187], v[90:93]
	v_mfma_f32_16x16x32_bf16 v[78:81], v[208:211], v[192:195], v[78:81]
	v_mfma_f32_16x16x32_bf16 v[74:77], v[216:219], v[192:195], v[74:77]
	v_mfma_f32_16x16x32_bf16 v[70:73], v[208:211], v[200:203], v[70:73]
	v_mfma_f32_16x16x32_bf16 v[66:69], v[216:219], v[200:203], v[66:69]
	s_setprio 0
	s_mov_b32 m0, s15
	v_lshl_add_u64 v[170:171], s[22:23], 0, v[134:135]
	s_barrier
	ds_read_b128 v[160:163], v143 offset:16384
	ds_read_b128 v[176:179], v143 offset:17408
	ds_read_b128 v[180:183], v143 offset:18432
	ds_read_b128 v[184:187], v143 offset:19456
	ds_read_b128 v[188:191], v143 offset:20480
	ds_read_b128 v[192:195], v143 offset:21504
	ds_read_b128 v[196:199], v143 offset:22528
	ds_read_b128 v[200:203], v143 offset:23552
	global_load_lds_dwordx4 v[170:171], off
	v_lshl_add_u64 v[220:221], s[22:23], 0, v[132:133]
	s_mov_b32 m0, s45
	s_nop 0
	global_load_lds_dwordx4 v[220:221], off
	s_barrier
	s_waitcnt lgkmcnt(0)
	s_setprio 1
	s_waitcnt lgkmcnt(0)
	v_mfma_f32_16x16x32_bf16 v[62:65], v[144:147], v[160:163], 0
	v_mfma_f32_16x16x32_bf16 v[58:61], v[152:155], v[160:163], 0
	v_mfma_f32_16x16x32_bf16 v[54:57], v[144:147], v[180:183], 0
	v_mfma_f32_16x16x32_bf16 v[50:53], v[152:155], v[180:183], 0
	v_mfma_f32_16x16x32_bf16 v[38:41], v[144:147], v[188:191], 0
	v_mfma_f32_16x16x32_bf16 v[34:37], v[152:155], v[188:191], 0
	v_mfma_f32_16x16x32_bf16 v[22:25], v[144:147], v[196:199], 0
	v_mfma_f32_16x16x32_bf16 v[18:21], v[152:155], v[196:199], 0
	v_mfma_f32_16x16x32_bf16 v[62:65], v[148:151], v[176:179], v[62:65]
	v_mfma_f32_16x16x32_bf16 v[58:61], v[156:159], v[176:179], v[58:61]
	v_mfma_f32_16x16x32_bf16 v[54:57], v[148:151], v[184:187], v[54:57]
	v_mfma_f32_16x16x32_bf16 v[50:53], v[156:159], v[184:187], v[50:53]
	v_mfma_f32_16x16x32_bf16 v[38:41], v[148:151], v[192:195], v[38:41]
	v_mfma_f32_16x16x32_bf16 v[34:37], v[156:159], v[192:195], v[34:37]
	v_mfma_f32_16x16x32_bf16 v[22:25], v[148:151], v[200:203], v[22:25]
	v_mfma_f32_16x16x32_bf16 v[18:21], v[156:159], v[200:203], v[18:21]
	s_setprio 0
	s_barrier
; #define PG8_STAGE(bufoff, gbase, voff) do { _Pragma("unroll") for (int _i = 0; _i < 2; ++_i) \
;         __builtin_amdgcn_global_load_lds((const unsigned*)((const char*)(gbase) + (voff)[_i]), (LAS unsigned*)(lds + (bufoff) + ldsw + _i * 8192), 16, 0, 0); } while (0)
; #define PG8_LDA(dst, b, h) do { _Pragma("unroll") for (int m = 0; m < 4; ++m) _Pragma("unroll") for (int k = 0; k < 2; ++k) dst[m][k] = *(const LAS bf16x8*)(lds + PG8_SA(b, h) + aoff + m * 2048 + k * 1024); } while (0)
; #define PG8_LDB(dst, b, h) do { _Pragma("unroll") for (int n = 0; n < 2; ++n) _Pragma("unroll") for (int k = 0; k < 2; ++k) dst[n][k] = *(const LAS bf16x8*)(lds + PG8_SB(b, h) + boff + n * 2048 + k * 1024); } while (0)
; #define PG8_MMA(ai, bj, At, Bt) do { __builtin_amdgcn_s_setprio(1); _Pragma("unroll") for (int m = 0; m < 4; ++m) _Pragma("unroll") for (int n = 0; n < 2; ++n) _Pragma("unroll") for (int k = 0; k < 2; ++k) \
;         acc[ai][bj][m][n] = __builtin_amdgcn_mfma_f32_16x16x32_bf16(Bt[n][k], At[m][k], acc[ai][bj][m][n], 0, 0, 0); __builtin_amdgcn_s_setprio(0); } while (0)
; #define PG8_WAIT_V(n) asm volatile("s_waitcnt vmcnt(" #n ")" ::: "memory")
; #define PG8_WAIT_L(n) asm volatile("s_waitcnt lgkmcnt(" #n ")" ::: "memory")
; #define PG8_BAR __builtin_amdgcn_s_barrier()
; #define PG8_SCHED __builtin_amdgcn_sched_barrier(0)
; template <class Epi>
; DI void gemm_phase(int wv, LAS unsigned char* lds, const GemmD g, const Epi& E) {
;     ...
;             PG8_STAGE(PG8_SB(0, 1), b2 + hstepB, voffB);
;             PG8_WAIT_V(6); PG8_BAR; PG8_MMA(1, 1, At, B1); PG8_BAR;
;             PG8_LDB(B0, 1, 0); PG8_SCHED; PG8_LDA(At, 1, 0); PG8_STAGE(PG8_SA(0, 1), a2 + hstepA, voffA);
;             PG8_WAIT_L(8); PG8_BAR; PG8_WAIT_L(0); PG8_MMA(0, 0, At, B0); PG8_BAR; PG8_SCHED;
;             PG8_LDB(B1, 1, 1); PG8_STAGE(PG8_SB(1, 0), b3, voffB);
;             PG8_BAR; PG8_WAIT_L(0); PG8_MMA(0, 1, At, B1); PG8_BAR;
	s_add_u32 s24, s24, s36
	s_addc_u32 s25, s25, 0
	s_add_i32 s2, s2, s37
	v_lshl_add_u64 v[222:223], s[24:25], 0, v[0:1]
	s_mov_b32 m0, s2
	v_lshl_add_u64 v[224:225], s[24:25], 0, v[130:131]
	global_load_lds_dwordx4 v[222:223], off
	s_add_i32 m0, s2, 0x2000
	s_nop 0
	global_load_lds_dwordx4 v[224:225], off
	s_waitcnt vmcnt(6)
	s_barrier
	s_setprio 1
	v_mfma_f32_16x16x32_bf16 v[46:49], v[204:207], v[160:163], 0
	v_mfma_f32_16x16x32_bf16 v[42:45], v[212:215], v[160:163], 0
	v_mfma_f32_16x16x32_bf16 v[30:33], v[204:207], v[180:183], 0
	v_mfma_f32_16x16x32_bf16 v[26:29], v[212:215], v[180:183], 0
	v_mfma_f32_16x16x32_bf16 v[14:17], v[204:207], v[188:191], 0
	v_mfma_f32_16x16x32_bf16 v[10:13], v[212:215], v[188:191], 0
	v_mfma_f32_16x16x32_bf16 v[6:9], v[204:207], v[196:199], 0
	v_mfma_f32_16x16x32_bf16 v[2:5], v[212:215], v[196:199], 0
	v_mfma_f32_16x16x32_bf16 v[46:49], v[208:211], v[176:179], v[46:49]
	v_mfma_f32_16x16x32_bf16 v[42:45], v[216:219], v[176:179], v[42:45]
	v_mfma_f32_16x16x32_bf16 v[30:33], v[208:211], v[184:187], v[30:33]
	v_mfma_f32_16x16x32_bf16 v[26:29], v[216:219], v[184:187], v[26:29]
	v_mfma_f32_16x16x32_bf16 v[14:17], v[208:211], v[192:195], v[14:17]
	v_mfma_f32_16x16x32_bf16 v[10:13], v[216:219], v[192:195], v[10:13]
	v_mfma_f32_16x16x32_bf16 v[6:9], v[208:211], v[200:203], v[6:9]
	v_mfma_f32_16x16x32_bf16 v[2:5], v[216:219], v[200:203], v[2:5]
	s_setprio 0
	s_add_i32 s2, 0, 0x18000
	v_add_u32_e32 v156, s2, v141
	s_barrier
	ds_read_b128 v[144:147], v156
	ds_read_b128 v[148:151], v156 offset:1024
	ds_read_b128 v[152:155], v156 offset:2048
	ds_read_b128 v[156:159], v156 offset:3072
	s_add_u32 s22, s22, 0x40000
	s_addc_u32 s23, s23, 0
	s_mov_b32 m0, s82
	v_lshl_add_u64 v[204:205], s[22:23], 0, v[134:135]
	ds_read_b128 v[160:163], v143 offset:32768
	ds_read_b128 v[176:179], v143 offset:33792
	ds_read_b128 v[180:183], v143 offset:34816
	ds_read_b128 v[184:187], v143 offset:35840
	ds_read_b128 v[188:191], v143 offset:36864
	ds_read_b128 v[192:195], v143 offset:37888
	ds_read_b128 v[196:199], v143 offset:38912
	ds_read_b128 v[200:203], v143 offset:39936
	global_load_lds_dwordx4 v[204:205], off
	v_lshl_add_u64 v[204:205], s[22:23], 0, v[132:133]
	s_mov_b32 m0, s83
	s_nop 0
	global_load_lds_dwordx4 v[204:205], off
	s_waitcnt lgkmcnt(8)
	s_barrier
	s_waitcnt lgkmcnt(0)
	s_setprio 1
	s_waitcnt lgkmcnt(0)
	v_mfma_f32_16x16x32_bf16 v[126:129], v[144:147], v[160:163], v[126:129]
	v_mfma_f32_16x16x32_bf16 v[122:125], v[152:155], v[160:163], v[122:125]
	v_mfma_f32_16x16x32_bf16 v[118:121], v[144:147], v[180:183], v[118:121]
	v_mfma_f32_16x16x32_bf16 v[114:117], v[152:155], v[180:183], v[114:117]
	v_mfma_f32_16x16x32_bf16 v[102:105], v[144:147], v[188:191], v[102:105]
	v_mfma_f32_16x16x32_bf16 v[98:101], v[152:155], v[188:191], v[98:101]
	v_mfma_f32_16x16x32_bf16 v[86:89], v[144:147], v[196:199], v[86:89]
	v_mfma_f32_16x16x32_bf16 v[82:85], v[152:155], v[196:199], v[82:85]
	v_mfma_f32_16x16x32_bf16 v[126:129], v[148:151], v[176:179], v[126:129]
	v_mfma_f32_16x16x32_bf16 v[122:125], v[156:159], v[176:179], v[122:125]
	v_mfma_f32_16x16x32_bf16 v[118:121], v[148:151], v[184:187], v[118:121]
	v_mfma_f32_16x16x32_bf16 v[114:117], v[156:159], v[184:187], v[114:117]
	v_mfma_f32_16x16x32_bf16 v[102:105], v[148:151], v[192:195], v[102:105]
	v_mfma_f32_16x16x32_bf16 v[98:101], v[156:159], v[192:195], v[98:101]
	v_mfma_f32_16x16x32_bf16 v[86:89], v[148:151], v[200:203], v[86:89]
	v_mfma_f32_16x16x32_bf16 v[82:85], v[156:159], v[200:203], v[82:85]
	s_setprio 0
	s_barrier
	s_add_i32 s3, 0, 0x1c000
	s_add_i32 s2, s2, s37
	v_add_u32_e32 v216, s3, v141
	v_lshl_add_u64 v[164:165], v[164:165], 0, s[58:59]
	s_mov_b32 m0, s2
	ds_read_b128 v[204:207], v216
	ds_read_b128 v[208:211], v216 offset:1024
	ds_read_b128 v[212:215], v216 offset:2048
	ds_read_b128 v[216:219], v216 offset:3072
	global_load_lds_dwordx4 v[164:165], off
	v_lshl_add_u64 v[164:165], v[168:169], 0, s[58:59]
	s_add_i32 m0, s2, 0x2000
	s_nop 0
	global_load_lds_dwordx4 v[164:165], off
	s_barrier
; #define PG8_STAGE(bufoff, gbase, voff) do { _Pragma("unroll") for (int _i = 0; _i < 2; ++_i) \
;         __builtin_amdgcn_global_load_lds((const unsigned*)((const char*)(gbase) + (voff)[_i]), (LAS unsigned*)(lds + (bufoff) + ldsw + _i * 8192), 16, 0, 0); } while (0)
; #define PG8_LDA(dst, b, h) do { _Pragma("unroll") for (int m = 0; m < 4; ++m) _Pragma("unroll") for (int k = 0; k < 2; ++k) dst[m][k] = *(const LAS bf16x8*)(lds + PG8_SA(b, h) + aoff + m * 2048 + k * 1024); } while (0)
; #define PG8_MMA(ai, bj, At, Bt) do { __builtin_amdgcn_s_setprio(1); _Pragma("unroll") for (int m = 0; m < 4; ++m) _Pragma("unroll") for (int n = 0; n < 2; ++n) _Pragma("unroll") for (int k = 0; k < 2; ++k) \
;         acc[ai][bj][m][n] = __builtin_amdgcn_mfma_f32_16x16x32_bf16(Bt[n][k], At[m][k], acc[ai][bj][m][n], 0, 0, 0); __builtin_amdgcn_s_setprio(0); } while (0)
; #define PG8_WAIT_V(n) asm volatile("s_waitcnt vmcnt(" #n ")" ::: "memory")
; #define PG8_WAIT_L(n) asm volatile("s_waitcnt lgkmcnt(" #n ")" ::: "memory")
; #define PG8_BAR __builtin_amdgcn_s_barrier()
; #define PG8_SCHED __builtin_amdgcn_sched_barrier(0)
; template <class Epi>
; DI void gemm_phase(int wv, LAS unsigned char* lds, const GemmD g, const Epi& E) {
;     ...
;             PG8_BAR; PG8_WAIT_L(0); PG8_MMA(0, 1, At, B1); PG8_BAR;
;             PG8_LDA(At, 1, 1); PG8_STAGE(PG8_SA(1, 0), a3, voffA);
;             PG8_BAR; PG8_WAIT_L(0); PG8_MMA(1, 0, At, B0); PG8_BAR; PG8_SCHED;
;             PG8_STAGE(PG8_SB(1, 1), b3 + hstepB, voffB);
;             PG8_WAIT_V(6); PG8_BAR; PG8_MMA(1, 1, At, B1); PG8_BAR;
	s_waitcnt lgkmcnt(0)
	s_setprio 1
	s_waitcnt lgkmcnt(0)
	v_mfma_f32_16x16x32_bf16 v[110:113], v[204:207], v[160:163], v[110:113]
	v_mfma_f32_16x16x32_bf16 v[106:109], v[212:215], v[160:163], v[106:109]
	v_mfma_f32_16x16x32_bf16 v[94:97], v[204:207], v[180:183], v[94:97]
	v_mfma_f32_16x16x32_bf16 v[90:93], v[212:215], v[180:183], v[90:93]
	v_mfma_f32_16x16x32_bf16 v[78:81], v[204:207], v[188:191], v[78:81]
	v_mfma_f32_16x16x32_bf16 v[74:77], v[212:215], v[188:191], v[74:77]
	v_mfma_f32_16x16x32_bf16 v[70:73], v[204:207], v[196:199], v[70:73]
	v_mfma_f32_16x16x32_bf16 v[66:69], v[212:215], v[196:199], v[66:69]
	v_mfma_f32_16x16x32_bf16 v[110:113], v[208:211], v[176:179], v[110:113]
	v_mfma_f32_16x16x32_bf16 v[106:109], v[216:219], v[176:179], v[106:109]
	v_mfma_f32_16x16x32_bf16 v[94:97], v[208:211], v[184:187], v[94:97]
	v_mfma_f32_16x16x32_bf16 v[90:93], v[216:219], v[184:187], v[90:93]
	v_mfma_f32_16x16x32_bf16 v[78:81], v[208:211], v[192:195], v[78:81]
	v_mfma_f32_16x16x32_bf16 v[74:77], v[216:219], v[192:195], v[74:77]
	v_mfma_f32_16x16x32_bf16 v[70:73], v[208:211], v[200:203], v[70:73]
	v_mfma_f32_16x16x32_bf16 v[66:69], v[216:219], v[200:203], v[66:69]
	s_setprio 0
	s_mov_b32 m0, s84
	v_lshl_add_u64 v[164:165], v[170:171], 0, s[58:59]
	s_barrier
	ds_read_b128 v[160:163], v143 offset:49152
	ds_read_b128 v[176:179], v143 offset:50176
	ds_read_b128 v[180:183], v143 offset:51200
	ds_read_b128 v[184:187], v143 offset:52224
	ds_read_b128 v[188:191], v143 offset:53248
	ds_read_b128 v[192:195], v143 offset:54272
	ds_read_b128 v[196:199], v143 offset:55296
	ds_read_b128 v[200:203], v143 offset:56320
	global_load_lds_dwordx4 v[164:165], off
	v_lshl_add_u64 v[164:165], v[220:221], 0, s[58:59]
	s_mov_b32 m0, s85
	s_nop 0
	global_load_lds_dwordx4 v[164:165], off
	s_barrier
	s_waitcnt lgkmcnt(0)
	s_setprio 1
	s_waitcnt lgkmcnt(0)
	v_mfma_f32_16x16x32_bf16 v[62:65], v[144:147], v[160:163], v[62:65]
	v_mfma_f32_16x16x32_bf16 v[58:61], v[152:155], v[160:163], v[58:61]
	v_mfma_f32_16x16x32_bf16 v[54:57], v[144:147], v[180:183], v[54:57]
	v_mfma_f32_16x16x32_bf16 v[50:53], v[152:155], v[180:183], v[50:53]
	v_mfma_f32_16x16x32_bf16 v[38:41], v[144:147], v[188:191], v[38:41]
	v_mfma_f32_16x16x32_bf16 v[34:37], v[152:155], v[188:191], v[34:37]
	v_mfma_f32_16x16x32_bf16 v[22:25], v[144:147], v[196:199], v[22:25]
	v_mfma_f32_16x16x32_bf16 v[18:21], v[152:155], v[196:199], v[18:21]
	v_mfma_f32_16x16x32_bf16 v[62:65], v[148:151], v[176:179], v[62:65]
	v_mfma_f32_16x16x32_bf16 v[58:61], v[156:159], v[176:179], v[58:61]
	v_mfma_f32_16x16x32_bf16 v[54:57], v[148:151], v[184:187], v[54:57]
	v_mfma_f32_16x16x32_bf16 v[50:53], v[156:159], v[184:187], v[50:53]
	v_mfma_f32_16x16x32_bf16 v[38:41], v[148:151], v[192:195], v[38:41]
	v_mfma_f32_16x16x32_bf16 v[34:37], v[156:159], v[192:195], v[34:37]
	v_mfma_f32_16x16x32_bf16 v[22:25], v[148:151], v[200:203], v[22:25]
	v_mfma_f32_16x16x32_bf16 v[18:21], v[156:159], v[200:203], v[18:21]
	s_setprio 0
	s_barrier
	s_add_i32 s2, s3, s37
	v_lshl_add_u64 v[144:145], v[222:223], 0, s[58:59]
	s_mov_b32 m0, s2
	s_nop 0
	global_load_lds_dwordx4 v[144:145], off
	v_lshl_add_u64 v[144:145], v[224:225], 0, s[58:59]
	s_add_i32 m0, s2, 0x2000
	s_nop 0
	global_load_lds_dwordx4 v[144:145], off
	s_waitcnt vmcnt(6)
	s_barrier
	s_setprio 1
	v_mfma_f32_16x16x32_bf16 v[46:49], v[204:207], v[160:163], v[46:49]
	v_mfma_f32_16x16x32_bf16 v[42:45], v[212:215], v[160:163], v[42:45]
	v_mfma_f32_16x16x32_bf16 v[30:33], v[204:207], v[180:183], v[30:33]
	v_mfma_f32_16x16x32_bf16 v[26:29], v[212:215], v[180:183], v[26:29]
	v_mfma_f32_16x16x32_bf16 v[14:17], v[204:207], v[188:191], v[14:17]
	v_mfma_f32_16x16x32_bf16 v[10:13], v[212:215], v[188:191], v[10:13]
	v_mfma_f32_16x16x32_bf16 v[6:9], v[204:207], v[196:199], v[6:9]
	v_mfma_f32_16x16x32_bf16 v[2:5], v[212:215], v[196:199], v[2:5]
	v_mfma_f32_16x16x32_bf16 v[46:49], v[208:211], v[176:179], v[46:49]
	v_mfma_f32_16x16x32_bf16 v[42:45], v[216:219], v[176:179], v[42:45]
	v_mfma_f32_16x16x32_bf16 v[30:33], v[208:211], v[184:187], v[30:33]
	v_mfma_f32_16x16x32_bf16 v[26:29], v[216:219], v[184:187], v[26:29]
	v_mfma_f32_16x16x32_bf16 v[14:17], v[208:211], v[192:195], v[14:17]
	v_mfma_f32_16x16x32_bf16 v[10:13], v[216:219], v[192:195], v[10:13]
	v_mfma_f32_16x16x32_bf16 v[6:9], v[208:211], v[200:203], v[6:9]
	v_mfma_f32_16x16x32_bf16 v[2:5], v[216:219], v[200:203], v[2:5]
	s_setprio 0
	s_add_i32 s95, s95, 2
	s_add_u32 s4, s4, 0x100
	s_addc_u32 s5, s5, 0
	s_add_u32 vcc_hi, vcc_hi, 0x100
	s_addc_u32 s75, s75, 0
	s_cmp_gt_u32 s95, 13
	s_barrier
	s_cbranch_scc0 .LBB0_99
	s_branch .Lgemm_epi_a

; DI unsigned pk2(float lo, float hi) { f32x2 f = {lo, hi}; bf2_t v = __builtin_convertvector(f, bf2_t); return __builtin_bit_cast(unsigned, v); }
; #define PG8_WAIT_V(n) asm volatile("s_waitcnt vmcnt(" #n ")" ::: "memory")
; #define PG8_BAR __builtin_amdgcn_s_barrier()
;     DI void operator()(const f32x4 (&acc)[2][2][4][2], const Unit& u, int wr, int wc, int fr, int fq) const {
;         const int row0 = u.pm * BM + wr * 64 + fr; const int col0 = u.pn * BM + wc * 32 + 8 * fq;
; #pragma unroll
;         for (int ai = 0; ai < 2; ++ai)
; #pragma unroll
;             for (int m = 0; m < 4; ++m) { bf16_t* rowp = O + (size_t)(row0 + ai * HALF + m * 16) * ldc + col0;
; #pragma unroll
;                 for (int bj = 0; bj < 2; ++bj) { f32x4 v0 = acc[ai][bj][m][0], v1 = acc[ai][bj][m][1];
;                     if (ACT == 1) {
; #pragma unroll
;                         for (int j = 0; j < 4; ++j) { float a = fmaxf(v0[j], 0.f), b = fmaxf(v1[j], 0.f); v0[j] = a * a; v1[j] = b * b; } }
;                     u32x4 w; w.x = pk2(v0[0], v0[1]); w.y = pk2(v0[2], v0[3]); w.z = pk2(v1[0], v1[1]); w.w = pk2(v1[2], v1[3]);
;                     *(u32x4*)(rowp + bj * HALF) = w; } }
; template <class Epi>
; DI void gemm_phase(int wv, LAS unsigned char* lds, const GemmD g, const Epi& E) {
;     ...
;         E(acc, cur, wr, wc, fr, fq);
;         if (!has_next) break;
; #pragma unroll
;         for (int a = 0; a < 2; ++a)
; #pragma unroll
;             for (int b = 0; b < 2; ++b)
; #pragma unroll
;                 for (int m = 0; m < 4; ++m)
; #pragma unroll
;                     for (int n = 0; n < 2; ++n) acc[a][b][m][n] = (f32x4){0.f, 0.f, 0.f, 0.f};
;         cur = nxt; cA = nA; cB = nB; ++ui;
;     }
;     PG8_WAIT_V(0);
;     if (wr == 0) PG8_BAR;
;     PG8_BAR;
.Lgemm_epi_a:
	v_lshl_add_u32 v148, s14, 8, v140
	v_lshl_or_b32 v144, s55, 8, v142
	v_ashrrev_i32_e32 v145, 31, v144
	v_mad_i64_i32 v[146:147], s[4:5], s12, v148, 0
	v_cvt_pk_bf16_f32 v110, v110, v111
	v_cvt_pk_bf16_f32 v111, v112, v113
	v_cvt_pk_bf16_f32 v112, v106, v107
	v_or_b32_e32 v106, 16, v148
	v_lshl_add_u64 v[146:147], v[146:147], 1, s[10:11]
	v_lshlrev_b64 v[144:145], 1, v[144:145]
	v_mad_i64_i32 v[106:107], s[4:5], s12, v106, 0
	v_cvt_pk_bf16_f32 v94, v94, v95
	v_cvt_pk_bf16_f32 v95, v96, v97
	v_cvt_pk_bf16_f32 v96, v90, v91
	v_or_b32_e32 v90, 32, v148
	v_lshl_add_u64 v[146:147], v[146:147], 0, v[144:145]
	v_cvt_pk_bf16_f32 v113, v108, v109
	v_lshl_add_u64 v[106:107], v[106:107], 1, s[10:11]
	v_mad_i64_i32 v[90:91], s[4:5], s12, v90, 0
	v_cvt_pk_bf16_f32 v78, v78, v79
	v_cvt_pk_bf16_f32 v79, v80, v81
	v_cvt_pk_bf16_f32 v80, v74, v75
	v_or_b32_e32 v74, 48, v148
	v_cvt_pk_bf16_f32 v70, v70, v71
	v_cvt_pk_bf16_f32 v71, v72, v73
	v_cvt_pk_bf16_f32 v72, v66, v67
	v_add_u32_e32 v66, 0x80, v148
	v_cvt_pk_bf16_f32 v126, v126, v127
	v_cvt_pk_bf16_f32 v127, v128, v129
	v_cvt_pk_bf16_f32 v128, v122, v123
	v_cvt_pk_bf16_f32 v129, v124, v125
	global_store_dwordx4 v[146:147], v[110:113], off offset:256
	v_cvt_pk_bf16_f32 v97, v92, v93
	v_lshl_add_u64 v[90:91], v[90:91], 1, s[10:11]
	v_lshl_add_u64 v[110:111], v[106:107], 0, v[144:145]
	v_mad_i64_i32 v[74:75], s[4:5], s12, v74, 0
	v_mad_i64_i32 v[66:67], s[4:5], s12, v66, 0
	v_cvt_pk_bf16_f32 v46, v46, v47
	v_cvt_pk_bf16_f32 v47, v48, v49
	v_cvt_pk_bf16_f32 v48, v42, v43
	v_add_u32_e32 v42, 0x90, v148
	global_store_dwordx4 v[146:147], v[126:129], off
	v_cvt_pk_bf16_f32 v106, v118, v119
	v_cvt_pk_bf16_f32 v107, v120, v121
	v_cvt_pk_bf16_f32 v108, v114, v115
	v_cvt_pk_bf16_f32 v109, v116, v117
	global_store_dwordx4 v[110:111], v[94:97], off offset:256
	v_cvt_pk_bf16_f32 v81, v76, v77
	v_lshl_add_u64 v[74:75], v[74:75], 1, s[10:11]
	v_lshl_add_u64 v[94:95], v[90:91], 0, v[144:145]
	v_lshl_add_u64 v[66:67], v[66:67], 1, s[10:11]
	v_mad_i64_i32 v[42:43], s[4:5], s12, v42, 0
	v_cvt_pk_bf16_f32 v30, v30, v31
	v_cvt_pk_bf16_f32 v31, v32, v33
	v_cvt_pk_bf16_f32 v32, v26, v27
	v_add_u32_e32 v26, 0xa0, v148
	global_store_dwordx4 v[110:111], v[106:109], off
	v_cvt_pk_bf16_f32 v90, v102, v103
	v_cvt_pk_bf16_f32 v91, v104, v105
	v_cvt_pk_bf16_f32 v92, v98, v99
	v_cvt_pk_bf16_f32 v93, v100, v101
	global_store_dwordx4 v[94:95], v[78:81], off offset:256
	v_cvt_pk_bf16_f32 v76, v82, v83
	v_cvt_pk_bf16_f32 v77, v84, v85
	v_lshl_add_u64 v[78:79], v[74:75], 0, v[144:145]
	v_cvt_pk_bf16_f32 v74, v86, v87
	v_cvt_pk_bf16_f32 v75, v88, v89
	v_cvt_pk_bf16_f32 v73, v68, v69
	v_lshl_add_u64 v[66:67], v[66:67], 0, v[144:145]
	v_cvt_pk_bf16_f32 v49, v44, v45
	v_lshl_add_u64 v[42:43], v[42:43], 1, s[10:11]
	v_mad_i64_i32 v[26:27], s[4:5], s12, v26, 0
	v_cvt_pk_bf16_f32 v14, v14, v15
	v_cvt_pk_bf16_f32 v15, v16, v17
	v_cvt_pk_bf16_f32 v16, v10, v11
	v_add_u32_e32 v10, 0xb0, v148
	global_store_dwordx4 v[94:95], v[90:93], off
	global_store_dwordx4 v[78:79], v[74:77], off
	global_store_dwordx4 v[78:79], v[70:73], off offset:256
	v_cvt_pk_bf16_f32 v62, v62, v63
	v_cvt_pk_bf16_f32 v63, v64, v65
	v_cvt_pk_bf16_f32 v64, v58, v59
	v_cvt_pk_bf16_f32 v65, v60, v61
	global_store_dwordx4 v[66:67], v[46:49], off offset:256
	v_cvt_pk_bf16_f32 v33, v28, v29
	v_lshl_add_u64 v[26:27], v[26:27], 1, s[10:11]
	v_lshl_add_u64 v[46:47], v[42:43], 0, v[144:145]
	v_mad_i64_i32 v[10:11], s[4:5], s12, v10, 0
	global_store_dwordx4 v[66:67], v[62:65], off
	v_cvt_pk_bf16_f32 v42, v54, v55
	v_cvt_pk_bf16_f32 v43, v56, v57
	v_cvt_pk_bf16_f32 v44, v50, v51
	v_cvt_pk_bf16_f32 v45, v52, v53
	global_store_dwordx4 v[46:47], v[30:33], off offset:256
	v_cvt_pk_bf16_f32 v17, v12, v13
	v_lshl_add_u64 v[10:11], v[10:11], 1, s[10:11]
	v_lshl_add_u64 v[30:31], v[26:27], 0, v[144:145]
	global_store_dwordx4 v[46:47], v[42:45], off
	v_cvt_pk_bf16_f32 v26, v38, v39
	v_cvt_pk_bf16_f32 v27, v40, v41
	v_cvt_pk_bf16_f32 v28, v34, v35
	v_cvt_pk_bf16_f32 v29, v36, v37
	global_store_dwordx4 v[30:31], v[14:17], off offset:256
	v_cvt_pk_bf16_f32 v12, v18, v19
	v_cvt_pk_bf16_f32 v13, v20, v21
	v_lshl_add_u64 v[14:15], v[10:11], 0, v[144:145]
	v_cvt_pk_bf16_f32 v10, v22, v23
	v_cvt_pk_bf16_f32 v11, v24, v25
	v_cvt_pk_bf16_f32 v6, v6, v7
	v_cvt_pk_bf16_f32 v7, v8, v9
	v_cvt_pk_bf16_f32 v8, v2, v3
	v_cvt_pk_bf16_f32 v9, v4, v5
	s_and_b64 vcc, exec, s[0:1]
	s_mov_b32 s55, s68
	s_mov_b32 s14, s16
	s_mov_b64 s[22:23], s[18:19]
	s_mov_b64 s[24:25], s[20:21]
	global_store_dwordx4 v[30:31], v[26:29], off
	global_store_dwordx4 v[14:15], v[10:13], off
	global_store_dwordx4 v[14:15], v[6:9], off offset:256
	s_cbranch_vccz .LBB0_94
	s_waitcnt vmcnt(0)
	s_cmpk_gt_u32 s35, 0xff
	v_readlane_b32 s68, v253, 13
	s_cbranch_scc1 .LBB0_83
	s_barrier
	s_branch .LBB0_83

; DI void gla_scan_phase(int wv, LAS unsigned char* lds, const bf16_t* qd, const bf16_t* kst, const bf16_t* sbuf, const bf16_t* vt, const float* decay, float* obuf) {
;     ...
;             SCAN_LOADI(0, vA, sB);
; #pragma nounroll
;             for (int c = 0; c < 64; c += 2) {
;                 SCAN_BODYI(c, vA, sB, nvA, nsB);
;                 SCAN_BODYI(c + 1, nvA, nsB, vA, sB);
;             }
.LBB0_195:
	v_lshl_add_u64 v[2:3], s[48:49], 0, v[116:117]
	global_load_dwordx4 v[82:85], v[2:3], off offset:128
	global_load_dwordx4 v[58:61], v[2:3], off offset:160
	global_load_dwordx4 v[90:93], v[2:3], off offset:192
	global_load_dwordx4 v[94:97], v[2:3], off offset:224
	v_lshl_add_u64 v[2:3], s[48:49], 0, v[118:119]
	s_brev_b32 s2, 40
	v_add_co_u32_e32 v2, vcc, s2, v2
	s_waitcnt vmcnt(4)
	v_mfma_f32_32x32x16_bf16 v[18:33], v[34:37], v[50:53], 0
	v_addc_co_u32_e32 v3, vcc, 0, v3, vcc
	global_load_dwordx4 v[86:89], v[2:3], off
	global_load_dwordx4 v[62:65], v[2:3], off offset:32
	v_lshl_add_u64 v[2:3], s[48:49], 0, v[120:121]
	global_load_dwordx4 v[98:101], v[2:3], off offset:-64
	global_load_dwordx4 v[102:105], v[2:3], off offset:-32
	global_load_dwordx4 v[106:109], v[2:3], off
	global_load_dwordx4 v[110:113], v[2:3], off offset:32
	s_add_i32 s22, s21, 3
	s_add_i32 s2, s21, 4
	v_mfma_f32_32x32x16_bf16 v[2:17], v[34:37], v[66:69], 0
	s_cmp_lt_u32 s22, 63
	s_cselect_b32 s2, s2, 63
	s_lshl_b32 s56, s2, 7
	s_lshl_b32 s2, s2, 12
	v_or_b32_e32 v0, s2, v178
	v_lshlrev_b32_e32 v0, 1, v0
	s_add_i32 s21, s21, 2
	v_mfma_f32_32x32x16_bf16 v[2:17], v[38:41], v[70:73], v[2:17]
	v_lshl_add_u64 v[116:117], v[116:117], 0, s[60:61]
	v_lshl_add_u64 v[118:119], v[118:119], 0, s[64:65]
	v_lshl_add_u64 v[120:121], v[120:121], 0, s[64:65]
	s_cmp_gt_u32 s21, 61
	v_mfma_f32_32x32x16_bf16 v[2:17], v[42:45], v[74:77], v[2:17]
	v_mfma_f32_32x32x16_bf16 v[18:33], v[38:41], v[54:57], v[18:33]
	v_mfma_f32_32x32x16_bf16 v[2:17], v[46:49], v[78:81], v[2:17]
	s_nop 10
	ds_write2st64_b32 v177, v18, v19 offset0:128 offset1:129
	ds_write2st64_b32 v177, v2, v3 offset0:144 offset1:145
	ds_write2st64_b32 v177, v20, v21 offset0:130 offset1:131
	ds_write2st64_b32 v177, v4, v5 offset0:146 offset1:147
	ds_write2st64_b32 v177, v22, v23 offset0:132 offset1:133
	ds_write2st64_b32 v177, v6, v7 offset0:148 offset1:149
	ds_write2st64_b32 v177, v24, v25 offset0:134 offset1:135
	ds_write2st64_b32 v177, v8, v9 offset0:150 offset1:151
	ds_write2st64_b32 v177, v26, v27 offset0:136 offset1:137
	ds_write2st64_b32 v177, v10, v11 offset0:152 offset1:153
	ds_write2st64_b32 v177, v28, v29 offset0:138 offset1:139
	ds_write2st64_b32 v177, v12, v13 offset0:154 offset1:155
	ds_write2st64_b32 v177, v30, v31 offset0:140 offset1:141
	ds_write2st64_b32 v177, v14, v15 offset0:156 offset1:157
	ds_write2st64_b32 v177, v32, v33 offset0:142 offset1:143
	ds_write2st64_b32 v177, v16, v17 offset0:158 offset1:159
	s_waitcnt lgkmcnt(0)
	s_barrier
	v_lshl_add_u64 v[2:3], v[114:115], 0, s[56:57]
	global_load_dwordx4 v[34:37], v[2:3], off
	global_load_dwordx4 v[38:41], v[2:3], off offset:32
	global_load_dwordx4 v[42:45], v[2:3], off offset:64
	global_load_dwordx4 v[46:49], v[2:3], off offset:96
	global_load_dwordx4 v[50:53], v0, s[18:19]
	global_load_dwordx4 v[54:57], v0, s[18:19] offset:32
	v_or_b32_e32 v0, s2, v180
	v_lshlrev_b32_e32 v0, 1, v0
	global_load_dwordx4 v[66:69], v0, s[18:19]
	global_load_dwordx4 v[70:73], v0, s[18:19] offset:32
	global_load_dwordx4 v[74:77], v0, s[18:19] offset:64
	global_load_dwordx4 v[78:81], v0, s[18:19] offset:96
	s_waitcnt vmcnt(10)
	v_mfma_f32_32x32x16_bf16 v[2:17], v[82:85], v[98:101], 0
	v_mfma_f32_32x32x16_bf16 v[2:17], v[58:61], v[102:105], v[2:17]
	v_mfma_f32_32x32x16_bf16 v[18:33], v[82:85], v[86:89], 0
	v_mfma_f32_32x32x16_bf16 v[2:17], v[90:93], v[106:109], v[2:17]
	v_mfma_f32_32x32x16_bf16 v[18:33], v[58:61], v[62:65], v[18:33]
	v_mfma_f32_32x32x16_bf16 v[2:17], v[94:97], v[110:113], v[2:17]
	s_nop 10
	ds_write2st64_b32 v179, v18, v19 offset1:1
	ds_write2st64_b32 v179, v2, v3 offset0:16 offset1:17
	ds_write2st64_b32 v179, v20, v21 offset0:2 offset1:3
	ds_write2st64_b32 v179, v4, v5 offset0:18 offset1:19
	ds_write2st64_b32 v179, v22, v23 offset0:4 offset1:5
	ds_write2st64_b32 v179, v6, v7 offset0:20 offset1:21
	ds_write2st64_b32 v179, v24, v25 offset0:6 offset1:7
	ds_write2st64_b32 v179, v8, v9 offset0:22 offset1:23
	ds_write2st64_b32 v179, v26, v27 offset0:8 offset1:9
	ds_write2st64_b32 v179, v10, v11 offset0:24 offset1:25
	ds_write2st64_b32 v179, v28, v29 offset0:10 offset1:11
	ds_write2st64_b32 v179, v12, v13 offset0:26 offset1:27
	ds_write2st64_b32 v179, v30, v31 offset0:12 offset1:13
	ds_write2st64_b32 v179, v14, v15 offset0:28 offset1:29
	ds_write2st64_b32 v179, v32, v33 offset0:14 offset1:15
	ds_write2st64_b32 v179, v16, v17 offset0:30 offset1:31
	s_waitcnt lgkmcnt(0)
	s_barrier
	s_cbranch_scc0 .LBB0_195

.LBB0_199:
	v_cvt_pk_bf16_f32 v34, v2, v3
	v_cvt_pk_bf16_f32 v35, v4, v5
	v_cvt_pk_bf16_f32 v36, v6, v7
	v_cvt_pk_bf16_f32 v37, v8, v9
	v_lshl_add_u64 v[18:19], s[48:49], 0, v[216:217]
	v_lshl_add_u64 v[20:21], s[48:49], 0, v[220:221]
	v_lshl_add_u64 v[38:39], s[48:49], 0, v[226:227]
	global_load_dwordx4 v[122:125], v[18:19], off
	global_load_dwordx4 v[126:129], v[20:21], off
	v_lshl_add_u64 v[18:19], s[48:49], 0, v[228:229]
	v_lshl_add_u64 v[20:21], s[48:49], 0, v[230:231]
	v_add_co_u32_e32 v146, vcc, s93, v38
	global_load_dwordx4 v[118:121], v[18:19], off offset:160
	global_load_dwordx4 v[114:117], v[18:19], off offset:192
	global_load_dwordx4 v[142:145], v[20:21], off offset:-32
	global_load_dwordx4 v[130:133], v[18:19], off offset:224
	global_load_dwordx4 v[138:141], v[20:21], off
	global_load_dwordx4 v[134:137], v[20:21], off offset:32
	s_waitcnt vmcnt(8)
	v_mfma_f32_32x32x16_bf16 v[18:33], v[34:37], v[94:97], 0
	v_addc_co_u32_e32 v147, vcc, 0, v39, vcc
	s_mov_b32 s2, 0x10008000
	v_add_co_u32_e32 v148, vcc, s2, v38
	v_cvt_pk_bf16_f32 v168, v10, v11
	s_nop 0
	v_addc_co_u32_e32 v149, vcc, 0, v39, vcc
	v_mfma_f32_32x32x16_bf16 v[34:49], v[34:37], v[102:105], 0
	global_load_dwordx2 v[94:95], v[146:147], off
	global_load_dwordx2 v[96:97], v[146:147], off offset:16
	global_load_dwordx2 v[102:103], v[146:147], off offset:32
	global_load_dwordx2 v[104:105], v[146:147], off offset:48
	v_cvt_pk_bf16_f32 v169, v12, v13
	v_cvt_pk_bf16_f32 v170, v14, v15
	v_cvt_pk_bf16_f32 v171, v16, v17
	v_pk_mul_f32 v[16:17], v[88:89], v[16:17]
	v_pk_mul_f32 v[12:13], v[84:85], v[12:13]
	v_pk_mul_f32 v[8:9], v[80:81], v[8:9]
	v_mfma_f32_32x32x16_bf16 v[18:33], v[168:171], v[90:93], v[18:33]
	global_load_dwordx2 v[90:91], v[148:149], off
	global_load_dwordx2 v[92:93], v[148:149], off offset:16
	global_load_dwordx2 v[162:163], v[148:149], off offset:32
	global_load_dwordx2 v[164:165], v[148:149], off offset:48
	v_mul_f32_e64 v4, v76, v4
	v_mul_f32_e64 v5, v77, v5
	v_pk_mul_f32 v[14:15], v[86:87], v[14:15]
	v_pk_mul_f32 v[10:11], v[82:83], v[10:11]
	v_pk_mul_f32 v[6:7], v[78:79], v[6:7]
	v_pk_mul_f32 v[2:3], v[74:75], v[2:3]
	v_lshl_add_u64 v[158:159], s[48:49], 0, v[224:225]
	v_mfma_f32_32x32x16_bf16 v[34:49], v[168:171], v[98:101], v[34:49]
	global_load_dwordx4 v[146:149], v[158:159], off offset:-64
	global_load_dwordx4 v[150:153], v[158:159], off offset:-32
	global_load_dwordx4 v[154:157], v[158:159], off
	s_nop 0
	global_load_dwordx4 v[158:161], v[158:159], off offset:32
	ds_write2st64_b32 v181, v18, v19 offset1:1
	s_nop 5
	ds_write2st64_b32 v181, v34, v35 offset0:16 offset1:17
	ds_write2st64_b32 v181, v20, v21 offset0:2 offset1:3
	ds_write2st64_b32 v181, v36, v37 offset0:18 offset1:19
	ds_write2st64_b32 v181, v22, v23 offset0:4 offset1:5
	ds_write2st64_b32 v181, v38, v39 offset0:20 offset1:21
	ds_write2st64_b32 v181, v24, v25 offset0:6 offset1:7
	ds_write2st64_b32 v181, v40, v41 offset0:22 offset1:23
	ds_write2st64_b32 v181, v26, v27 offset0:8 offset1:9
	ds_write2st64_b32 v181, v42, v43 offset0:24 offset1:25
	ds_write2st64_b32 v181, v28, v29 offset0:10 offset1:11
	ds_write2st64_b32 v181, v44, v45 offset0:26 offset1:27
	ds_write2st64_b32 v181, v30, v31 offset0:12 offset1:13
	ds_write2st64_b32 v181, v46, v47 offset0:28 offset1:29
	ds_write2st64_b32 v181, v32, v33 offset0:14 offset1:15
	ds_write2st64_b32 v181, v48, v49 offset0:30 offset1:31
	v_mfma_f32_32x32x16_bf16 v[2:17], v[54:57], v[50:53], v[2:17]
	s_waitcnt lgkmcnt(0)
	s_barrier
	v_add_u32_e32 v183, s30, v177
	ds_read2st64_b32 v[18:19], v183 offset1:1
	ds_read2st64_b32 v[20:21], v183 offset0:2 offset1:3
	ds_read2st64_b32 v[22:23], v183 offset0:32 offset1:33
	ds_read2st64_b32 v[24:25], v183 offset0:34 offset1:35
	ds_read2st64_b32 v[26:27], v183 offset0:64 offset1:65
	ds_read2st64_b32 v[28:29], v183 offset0:66 offset1:67
	ds_read2st64_b32 v[30:31], v183 offset0:96 offset1:97
	ds_read2st64_b32 v[32:33], v183 offset0:98 offset1:99
	ds_read2st64_b32 v[34:35], v183 offset0:128 offset1:129
	ds_read2st64_b32 v[36:37], v183 offset0:130 offset1:131
	s_waitcnt lgkmcnt(0)
	v_pk_add_f32 v[20:21], v[20:21], 0 op_sel_hi:[1,0]
	v_pk_add_f32 v[18:19], v[18:19], 0 op_sel_hi:[1,0]
	v_mfma_f32_32x32x16_bf16 v[2:17], v[66:69], v[70:73], v[2:17]
	v_add_f32_e64 v18, v18, v22
	v_add_f32_e64 v19, v19, v23
	v_add_f32_e64 v20, v20, v24
	v_add_f32_e64 v21, v21, v25
	v_add_f32_e64 v18, v18, v26
	v_add_f32_e64 v19, v19, v27
	v_pk_add_f32 v[20:21], v[20:21], v[28:29]
	v_pk_add_f32 v[18:19], v[18:19], v[30:31]
	v_pk_add_f32 v[20:21], v[20:21], v[32:33]
	v_pk_add_f32 v[18:19], v[18:19], v[34:35]
	v_mfma_f32_32x32x16_bf16 v[2:17], v[58:61], v[62:65], v[2:17]
	v_add_f32_e64 v20, v20, v36
	v_add_f32_e64 v21, v21, v37
	v_lshl_add_u64 v[22:23], s[48:49], 0, v[218:219]
	global_store_dwordx4 v[22:23], v[18:21], off offset:-32
	v_add_u32_e32 v185, s31, v177
	ds_read2st64_b32 v[18:19], v185 offset1:1
	ds_read2st64_b32 v[20:21], v185 offset0:2 offset1:3
	ds_read2st64_b32 v[24:25], v185 offset0:32 offset1:33
	ds_read2st64_b32 v[26:27], v185 offset0:34 offset1:35
	ds_read2st64_b32 v[28:29], v185 offset0:64 offset1:65
	ds_read2st64_b32 v[30:31], v185 offset0:66 offset1:67
	ds_read2st64_b32 v[32:33], v185 offset0:96 offset1:97
	ds_read2st64_b32 v[34:35], v185 offset0:98 offset1:99
	ds_read2st64_b32 v[36:37], v185 offset0:128 offset1:129
	ds_read2st64_b32 v[38:39], v185 offset0:130 offset1:131
	s_waitcnt lgkmcnt(9)
	v_pk_add_f32 v[18:19], v[18:19], 0 op_sel_hi:[1,0]
	v_mfma_f32_32x32x16_bf16 v[2:17], v[106:109], v[110:113], v[2:17]
	s_waitcnt lgkmcnt(8)
	v_add_f32_e64 v20, v20, 0
	v_add_f32_e64 v21, v21, 0
	s_waitcnt lgkmcnt(7)
	v_add_f32_e64 v18, v18, v24
	v_add_f32_e64 v19, v19, v25
	s_waitcnt lgkmcnt(6)
	v_pk_add_f32 v[20:21], v[20:21], v[26:27]
	s_waitcnt lgkmcnt(5)
	v_pk_add_f32 v[18:19], v[18:19], v[28:29]
	s_waitcnt lgkmcnt(4)
	v_pk_add_f32 v[20:21], v[20:21], v[30:31]
	s_waitcnt lgkmcnt(3)
	v_pk_add_f32 v[18:19], v[18:19], v[32:33]
	s_waitcnt lgkmcnt(2)
	v_pk_add_f32 v[20:21], v[20:21], v[34:35]
	s_waitcnt lgkmcnt(1)
	v_pk_add_f32 v[18:19], v[18:19], v[36:37]
	v_cvt_pk_bf16_f32 v34, v2, v3
	v_cvt_pk_bf16_f32 v35, v4, v5
	v_cvt_pk_bf16_f32 v36, v6, v7
	v_cvt_pk_bf16_f32 v37, v8, v9
	s_add_i32 s15, s14, 3
	s_add_i32 s2, s14, 4
	s_waitcnt lgkmcnt(0)
	v_pk_add_f32 v[20:21], v[20:21], v[38:39]
	s_cmp_lt_u32 s15, 63
	global_store_dwordx4 v[22:23], v[18:21], off
	s_cselect_b32 s2, s2, 63
	v_lshl_or_b32 v0, s2, 6, v176
	s_waitcnt vmcnt(12)
	v_mfma_f32_32x32x16_bf16 v[18:33], v[34:37], v[94:97], 0
	v_lshlrev_b32_e32 v0, 1, v0
	s_lshl_b32 s56, s2, 7
	v_lshl_add_u64 v[38:39], v[212:213], 0, s[56:57]
	global_load_dwordx4 v[50:53], v0, s[12:13]
	global_load_dwordx4 v[54:57], v[38:39], off
	v_lshl_add_u64 v[40:41], v[210:211], 0, s[56:57]
	v_lshl_or_b32 v0, s2, 16, v214
	v_cvt_pk_bf16_f32 v168, v10, v11
	v_cvt_pk_bf16_f32 v169, v12, v13
	v_cvt_pk_bf16_f32 v170, v14, v15
	v_cvt_pk_bf16_f32 v171, v16, v17
	global_load_dwordx4 v[66:69], v[38:39], off offset:32
	global_load_dwordx4 v[58:61], v[38:39], off offset:64
	global_load_dwordx4 v[62:65], v[40:41], off offset:64
	global_load_dwordx4 v[110:113], v[40:41], off offset:96
	global_load_dwordx4 v[70:73], v[40:41], off offset:32
	global_load_dwordx4 v[106:109], v[38:39], off offset:96
	v_lshl_add_u64 v[38:39], s[18:19], 0, v[0:1]
	v_add_co_u32_e32 v74, vcc, s71, v38
	s_waitcnt vmcnt(18)
	v_mfma_f32_32x32x16_bf16 v[18:33], v[168:171], v[102:105], v[18:33]
	v_addc_co_u32_e32 v75, vcc, 0, v39, vcc
	s_waitcnt vmcnt(10)
	v_mul_f32_e64 v16, v160, v16
	v_mul_f32_e64 v17, v161, v17
	v_mul_f32_e64 v14, v158, v14
	v_mul_f32_e64 v15, v159, v15
	v_pk_mul_f32 v[12:13], v[156:157], v[12:13]
	v_pk_mul_f32 v[10:11], v[154:155], v[10:11]
	v_pk_mul_f32 v[8:9], v[152:153], v[8:9]
	v_mfma_f32_32x32x16_bf16 v[34:49], v[34:37], v[90:93], 0
	global_load_dwordx2 v[94:95], v0, s[18:19]
	global_load_dwordx2 v[96:97], v0, s[18:19] offset:16
	global_load_dwordx2 v[90:91], v0, s[18:19] offset:32
	global_load_dwordx2 v[92:93], v0, s[18:19] offset:48
	v_lshl_or_b32 v0, s2, 9, v182
	v_lshl_add_u64 v[86:87], v[0:1], 2, s[20:21]
	global_load_dwordx2 v[102:103], v[74:75], off
	global_load_dwordx2 v[104:105], v[74:75], off offset:16
	global_load_dwordx2 v[98:99], v[74:75], off offset:32
	global_load_dwordx2 v[100:101], v[74:75], off offset:48
	s_nop 0
	global_load_dwordx4 v[74:77], v[86:87], off
	global_load_dwordx4 v[78:81], v[86:87], off offset:32
	global_load_dwordx4 v[82:85], v[86:87], off offset:64
	s_nop 0
	global_load_dwordx4 v[86:89], v[86:87], off offset:96
	v_pk_mul_f32 v[6:7], v[150:151], v[6:7]
	v_pk_mul_f32 v[4:5], v[148:149], v[4:5]
	v_pk_mul_f32 v[2:3], v[146:147], v[2:3]
	v_mfma_f32_32x32x16_bf16 v[34:49], v[168:171], v[162:165], v[34:49]
	ds_write2st64_b32 v181, v18, v19 offset0:160 offset1:161
	s_nop 10
	ds_write2st64_b32 v181, v34, v35 offset0:176 offset1:177
	ds_write2st64_b32 v181, v20, v21 offset0:162 offset1:163
	ds_write2st64_b32 v181, v36, v37 offset0:178 offset1:179
	ds_write2st64_b32 v181, v22, v23 offset0:164 offset1:165
	ds_write2st64_b32 v181, v38, v39 offset0:180 offset1:181
	ds_write2st64_b32 v181, v24, v25 offset0:166 offset1:167
	ds_write2st64_b32 v181, v40, v41 offset0:182 offset1:183
	ds_write2st64_b32 v181, v26, v27 offset0:168 offset1:169
	ds_write2st64_b32 v181, v42, v43 offset0:184 offset1:185
	ds_write2st64_b32 v181, v28, v29 offset0:170 offset1:171
	ds_write2st64_b32 v181, v44, v45 offset0:186 offset1:187
	ds_write2st64_b32 v181, v30, v31 offset0:172 offset1:173
	ds_write2st64_b32 v181, v46, v47 offset0:188 offset1:189
	ds_write2st64_b32 v181, v32, v33 offset0:174 offset1:175
	ds_write2st64_b32 v181, v48, v49 offset0:190 offset1:191
	v_mfma_f32_32x32x16_bf16 v[2:17], v[126:129], v[122:125], v[2:17]
	s_waitcnt lgkmcnt(0)
	s_barrier
; DI void gla_scan_phase(int wv, LAS unsigned char* lds, const bf16_t* qd, const bf16_t* kst, const bf16_t* sbuf, const bf16_t* vt, const float* decay, float* obuf) {
;     ...
;             SCAN_LOADC(0, vA, kA, qB, dc);
; #pragma nounroll
;             for (int c = 0; c < 64; c += 2) {
;                 SCAN_BODYC(c, vA, kA, qB, dc, nvA, nkA, nqB, ndc);
;                 SCAN_BODYC(c + 1, nvA, nkA, nqB, ndc, vA, kA, qB, dc);
;             }
	ds_read2st64_b32 v[18:19], v183 offset0:160 offset1:161
	ds_read2st64_b32 v[20:21], v183 offset0:162 offset1:163
	ds_read2st64_b32 v[22:23], v183 offset0:192 offset1:193
	ds_read2st64_b32 v[24:25], v183 offset0:194 offset1:195
	ds_read2st64_b32 v[26:27], v183 offset0:224 offset1:225
	ds_read2st64_b32 v[28:29], v183 offset0:226 offset1:227
	v_add_u32_e32 v0, s35, v177
	v_add_u32_e32 v31, s36, v177
	v_add_u32_e32 v32, s37, v177
	v_mfma_f32_32x32x16_bf16 v[2:17], v[142:145], v[118:121], v[2:17]
	v_add_u32_e32 v33, s38, v177
	v_add_u32_e32 v34, s39, v177
	v_add_u32_e32 v35, s40, v177
	v_add_u32_e32 v36, s41, v177
	v_add_u32_e32 v37, s42, v177
	ds_read_b32 v30, v0 offset:40960
	ds_read_b32 v31, v31 offset:40960
	ds_read_b32 v32, v32 offset:40960
	ds_read_b32 v33, v33 offset:40960
	ds_read_b32 v34, v34 offset:40960
	ds_read_b32 v35, v35 offset:40960
	ds_read_b32 v36, v36 offset:40960
	ds_read_b32 v37, v37 offset:40960
	s_waitcnt lgkmcnt(12)
	v_pk_add_f32 v[20:21], v[20:21], 0 op_sel_hi:[1,0]
	v_mfma_f32_32x32x16_bf16 v[2:17], v[138:141], v[114:117], v[2:17]
	v_add_f32_e64 v18, v18, 0
	v_add_f32_e64 v19, v19, 0
	s_waitcnt lgkmcnt(10)
	v_add_f32_e64 v20, v20, v24
	v_add_f32_e64 v21, v21, v25
	v_pk_add_f32 v[18:19], v[18:19], v[22:23]
	s_waitcnt lgkmcnt(8)
	v_pk_add_f32 v[20:21], v[20:21], v[28:29]
	v_pk_add_f32 v[18:19], v[18:19], v[26:27]
	v_lshl_add_u64 v[22:23], s[48:49], 0, v[222:223]
	s_waitcnt lgkmcnt(6)
	v_pk_add_f32 v[18:19], v[18:19], v[30:31]
	s_waitcnt lgkmcnt(4)
	v_pk_add_f32 v[20:21], v[20:21], v[32:33]
	v_add_co_u32_e32 v22, vcc, s94, v22
	s_waitcnt lgkmcnt(0)
	v_pk_add_f32 v[20:21], v[20:21], v[36:37]
	v_pk_add_f32 v[18:19], v[18:19], v[34:35]
	v_addc_co_u32_e32 v23, vcc, 0, v23, vcc
	global_store_dwordx4 v[22:23], v[18:21], off
	ds_read2st64_b32 v[18:19], v185 offset0:160 offset1:161
	ds_read2st64_b32 v[20:21], v185 offset0:162 offset1:163
	ds_read2st64_b32 v[24:25], v185 offset0:192 offset1:193
	ds_read2st64_b32 v[26:27], v185 offset0:194 offset1:195
	ds_read2st64_b32 v[28:29], v185 offset0:224 offset1:225
	ds_read2st64_b32 v[30:31], v185 offset0:226 offset1:227
	v_mfma_f32_32x32x16_bf16 v[2:17], v[134:137], v[130:133], v[2:17]
	v_add_u32_e32 v0, s43, v177
	v_add_u32_e32 v33, s44, v177
	v_add_u32_e32 v34, s45, v177
	v_add_u32_e32 v35, s84, v177
	v_add_u32_e32 v36, s34, v177
	v_add_u32_e32 v37, s85, v177
	v_add_u32_e32 v38, s86, v177
	v_add_u32_e32 v39, s87, v177
	ds_read_b32 v32, v0 offset:40960
	ds_read_b32 v33, v33 offset:40960
	ds_read_b32 v34, v34 offset:40960
	ds_read_b32 v35, v35 offset:40960
	ds_read_b32 v36, v36 offset:40960
	ds_read_b32 v37, v37 offset:40960
	ds_read_b32 v38, v38 offset:40960
	ds_read_b32 v39, v39 offset:40960
	s_waitcnt lgkmcnt(12)
	v_pk_add_f32 v[20:21], v[20:21], 0 op_sel_hi:[1,0]
	v_pk_add_f32 v[18:19], v[18:19], 0 op_sel_hi:[1,0]
	s_waitcnt lgkmcnt(10)
	v_pk_add_f32 v[20:21], v[20:21], v[26:27]
	v_pk_add_f32 v[18:19], v[18:19], v[24:25]
	s_waitcnt lgkmcnt(8)
	v_pk_add_f32 v[20:21], v[20:21], v[30:31]
	v_pk_add_f32 v[18:19], v[18:19], v[28:29]
	s_mov_b64 s[16:17], 0x1000
	s_waitcnt lgkmcnt(6)
	v_pk_add_f32 v[18:19], v[18:19], v[32:33]
	s_waitcnt lgkmcnt(4)
	v_pk_add_f32 v[20:21], v[20:21], v[34:35]
	s_add_i32 s14, s14, 2
	v_lshl_add_u64 v[224:225], v[224:225], 0, s[16:17]
	s_mov_b64 s[16:17], 0x20000
	s_waitcnt lgkmcnt(0)
	v_pk_add_f32 v[20:21], v[20:21], v[38:39]
	v_pk_add_f32 v[18:19], v[18:19], v[36:37]
	v_lshl_add_u64 v[216:217], v[216:217], 0, s[60:61]
	v_lshl_add_u64 v[218:219], v[218:219], 0, s[66:67]
	v_lshl_add_u64 v[220:221], v[220:221], 0, s[60:61]
	v_lshl_add_u64 v[222:223], v[222:223], 0, s[66:67]
	v_lshl_add_u64 v[226:227], v[226:227], 0, s[16:17]
	v_lshl_add_u64 v[228:229], v[228:229], 0, s[60:61]
	v_lshl_add_u64 v[230:231], v[230:231], 0, s[60:61]
	s_cmp_gt_u32 s14, 61
	global_store_dwordx4 v[22:23], v[18:21], off offset:32
	s_cbranch_scc0 .LBB0_199
	v_mov_b64_e32 v[228:229], 0x800
	s_branch .LBB0_187

; #define PG8_STAGE(bufoff, gbase, voff) do { _Pragma("unroll") for (int _i = 0; _i < 2; ++_i) \
;         __builtin_amdgcn_global_load_lds((const unsigned*)((const char*)(gbase) + (voff)[_i]), (LAS unsigned*)(lds + (bufoff) + ldsw + _i * 8192), 16, 0, 0); } while (0)
; #define PG8_LDA(dst, b, h) do { _Pragma("unroll") for (int m = 0; m < 4; ++m) _Pragma("unroll") for (int k = 0; k < 2; ++k) dst[m][k] = *(const LAS bf16x8*)(lds + PG8_SA(b, h) + aoff + m * 2048 + k * 1024); } while (0)
; #define PG8_LDB(dst, b, h) do { _Pragma("unroll") for (int n = 0; n < 2; ++n) _Pragma("unroll") for (int k = 0; k < 2; ++k) dst[n][k] = *(const LAS bf16x8*)(lds + PG8_SB(b, h) + boff + n * 2048 + k * 1024); } while (0)
; #define PG8_MMA(ai, bj, At, Bt) do { __builtin_amdgcn_s_setprio(1); _Pragma("unroll") for (int m = 0; m < 4; ++m) _Pragma("unroll") for (int n = 0; n < 2; ++n) _Pragma("unroll") for (int k = 0; k < 2; ++k) \
;         acc[ai][bj][m][n] = __builtin_amdgcn_mfma_f32_16x16x32_bf16(Bt[n][k], At[m][k], acc[ai][bj][m][n], 0, 0, 0); __builtin_amdgcn_s_setprio(0); } while (0)
; #define PG8_WAIT_L(n) asm volatile("s_waitcnt lgkmcnt(" #n ")" ::: "memory")
; template <class Epi>
; DI void gemm_phase(int wv, LAS unsigned char* lds, const GemmD g, const Epi& E) {
;     ...
;         const bool has_next = S.next(ui + 1, nxt);
;         const char* nA = has_next ? (const char*)g.A + (size_t)nxt.pm * 256 * g.lda * 2 : cA; const char* nB = has_next ? (const char*)g.Bt + PG8_BROW(nxt.pn) * (size_t)g.ldb * 2 : cB;
;         for (int t = 0; t < nt; t += 2) {
;             const bool last = (t == nt - 2);
;             const char* a1 = cA + (size_t)(t + 1) * kstep;
;             const char* a2 = last ? nA : cA + (size_t)(t + 2) * kstep; const char* b2 = last ? nB : cB + (size_t)(t + 2) * kstep;
;             const char* a3 = a2 + kstep; const char* b3 = b2 + kstep;
;             PG8_LDB(B0, 0, 0); PG8_SCHED; PG8_LDA(At, 0, 0); PG8_STAGE(PG8_SA(1, 1), a1 + hstepA, voffA);
;             PG8_WAIT_L(8); PG8_BAR; PG8_WAIT_L(0); PG8_MMA(0, 0, At, B0); PG8_BAR; PG8_SCHED;
;             PG8_LDB(B1, 0, 1); PG8_STAGE(PG8_SB(0, 0), b2, voffB);
;             PG8_BAR; PG8_WAIT_L(0); PG8_MMA(0, 1, At, B1); PG8_BAR;
;             PG8_LDA(At, 0, 1); PG8_STAGE(PG8_SA(0, 0), a2, voffA);
;             PG8_BAR; PG8_WAIT_L(0); PG8_MMA(1, 0, At, B0); PG8_BAR; PG8_SCHED;
.LBB0_489:
	s_ashr_i32 s7, s6, 31
	v_cmp_lt_i64_e32 vcc, s[8:9], v[228:229]
	s_lshl_b64 s[8:9], s[6:7], 19
	s_add_u32 s8, s76, s8
	s_addc_u32 s9, s78, s9
	s_and_b64 s[16:17], vcc, exec
	s_cselect_b32 s7, s9, s27
	s_cselect_b32 s13, s8, s26
	s_lshl_b32 s16, s86, 8
	s_ashr_i32 s17, s16, 31
	s_lshl_b64 s[16:17], s[16:17], 11
	s_add_u32 s22, s39, s16
	s_addc_u32 s23, s40, s17
	s_and_b64 s[16:17], vcc, exec
	s_cselect_b32 s16, s23, s29
	s_cselect_b32 s17, s22, s28
	s_add_u32 s26, s26, 0x40080
	s_addc_u32 s27, s27, 0
	s_add_u32 s36, s28, 0x100
	s_addc_u32 s38, s29, 0
	s_mov_b32 s41, -2
	s_add_u32 s2, s26, 0xfffc0080
	s_addc_u32 s3, s27, -1
	s_add_i32 s18, 0, 0x10000
	v_add_u32_e32 v140, s18, v144
	ds_read_b128 v[148:151], v140
	ds_read_b128 v[152:155], v140 offset:1024
	ds_read_b128 v[156:159], v140 offset:2048
	ds_read_b128 v[160:163], v140 offset:3072
	s_cmp_eq_u32 s41, 12
	s_cselect_b32 s31, s7, s3
	s_cselect_b32 s30, s13, s2
	s_cselect_b32 s29, s16, s38
	s_cselect_b32 s28, s17, s36
	v_lshl_add_u64 v[140:141], s[26:27], 0, v[136:137]
	s_add_i32 m0, s25, 0xc000
	ds_read_b128 v[168:171], v146
	ds_read_b128 v[176:179], v146 offset:1024
	ds_read_b128 v[180:183], v146 offset:2048
	ds_read_b128 v[184:187], v146 offset:3072
	ds_read_b128 v[188:191], v146 offset:4096
	ds_read_b128 v[192:195], v146 offset:5120
	ds_read_b128 v[196:199], v146 offset:6144
	ds_read_b128 v[200:203], v146 offset:7168
	global_load_lds_dwordx4 v[140:141], off
	v_lshl_add_u64 v[140:141], s[26:27], 0, v[138:139]
	s_add_i32 m0, s25, 0xe000
	s_nop 0
	global_load_lds_dwordx4 v[140:141], off
	s_waitcnt lgkmcnt(8)
	s_barrier
	s_waitcnt lgkmcnt(0)
	s_setprio 1
	s_waitcnt lgkmcnt(0)
	v_mfma_f32_16x16x32_bf16 v[126:129], v[148:151], v[168:171], 0
	v_mfma_f32_16x16x32_bf16 v[122:125], v[156:159], v[168:171], 0
	v_mfma_f32_16x16x32_bf16 v[110:113], v[148:151], v[180:183], 0
	v_mfma_f32_16x16x32_bf16 v[106:109], v[156:159], v[180:183], 0
	v_mfma_f32_16x16x32_bf16 v[94:97], v[148:151], v[188:191], 0
	v_mfma_f32_16x16x32_bf16 v[90:93], v[156:159], v[188:191], 0
	v_mfma_f32_16x16x32_bf16 v[78:81], v[148:151], v[196:199], 0
	v_mfma_f32_16x16x32_bf16 v[74:77], v[156:159], v[196:199], 0
	v_mfma_f32_16x16x32_bf16 v[126:129], v[152:155], v[176:179], v[126:129]
	v_mfma_f32_16x16x32_bf16 v[122:125], v[160:163], v[176:179], v[122:125]
	v_mfma_f32_16x16x32_bf16 v[110:113], v[152:155], v[184:187], v[110:113]
	v_mfma_f32_16x16x32_bf16 v[106:109], v[160:163], v[184:187], v[106:109]
	v_mfma_f32_16x16x32_bf16 v[94:97], v[152:155], v[192:195], v[94:97]
	v_mfma_f32_16x16x32_bf16 v[90:93], v[160:163], v[192:195], v[90:93]
	v_mfma_f32_16x16x32_bf16 v[78:81], v[152:155], v[200:203], v[78:81]
	v_mfma_f32_16x16x32_bf16 v[74:77], v[160:163], v[200:203], v[74:77]
	s_setprio 0
	s_barrier
	s_add_i32 s2, 0, 0x14000
	v_add_u32_e32 v140, s2, v144
	s_add_i32 s3, s18, s79
	ds_read_b128 v[204:207], v140
	ds_read_b128 v[208:211], v140 offset:1024
	ds_read_b128 v[212:215], v140 offset:2048
	ds_read_b128 v[216:219], v140 offset:3072
	v_lshl_add_u64 v[140:141], s[28:29], 0, v[0:1]
	s_mov_b32 m0, s3
	v_lshl_add_u64 v[164:165], s[28:29], 0, v[134:135]
	global_load_lds_dwordx4 v[140:141], off
	s_add_i32 m0, s3, 0x2000
	s_nop 0
	global_load_lds_dwordx4 v[164:165], off
	s_barrier
	s_waitcnt lgkmcnt(0)
	s_setprio 1
	s_waitcnt lgkmcnt(0)
	v_mfma_f32_16x16x32_bf16 v[118:121], v[204:207], v[168:171], 0
	v_mfma_f32_16x16x32_bf16 v[114:117], v[212:215], v[168:171], 0
	v_mfma_f32_16x16x32_bf16 v[102:105], v[204:207], v[180:183], 0
	v_mfma_f32_16x16x32_bf16 v[98:101], v[212:215], v[180:183], 0
	v_mfma_f32_16x16x32_bf16 v[86:89], v[204:207], v[188:191], 0
	v_mfma_f32_16x16x32_bf16 v[82:85], v[212:215], v[188:191], 0
	v_mfma_f32_16x16x32_bf16 v[70:73], v[204:207], v[196:199], 0
	v_mfma_f32_16x16x32_bf16 v[66:69], v[212:215], v[196:199], 0
	v_mfma_f32_16x16x32_bf16 v[118:121], v[208:211], v[176:179], v[118:121]
	v_mfma_f32_16x16x32_bf16 v[114:117], v[216:219], v[176:179], v[114:117]
	v_mfma_f32_16x16x32_bf16 v[102:105], v[208:211], v[184:187], v[102:105]
	v_mfma_f32_16x16x32_bf16 v[98:101], v[216:219], v[184:187], v[98:101]
	v_mfma_f32_16x16x32_bf16 v[86:89], v[208:211], v[192:195], v[86:89]
	v_mfma_f32_16x16x32_bf16 v[82:85], v[216:219], v[192:195], v[82:85]
	v_mfma_f32_16x16x32_bf16 v[70:73], v[208:211], v[200:203], v[70:73]
	v_mfma_f32_16x16x32_bf16 v[66:69], v[216:219], v[200:203], v[66:69]
	s_setprio 0
	s_mov_b32 m0, s25
	v_lshl_add_u64 v[220:221], s[30:31], 0, v[130:131]
	s_barrier
	ds_read_b128 v[168:171], v146 offset:16384
	ds_read_b128 v[176:179], v146 offset:17408
	ds_read_b128 v[180:183], v146 offset:18432
	ds_read_b128 v[184:187], v146 offset:19456
	ds_read_b128 v[188:191], v146 offset:20480
	ds_read_b128 v[192:195], v146 offset:21504
	ds_read_b128 v[196:199], v146 offset:22528
	ds_read_b128 v[200:203], v146 offset:23552
	global_load_lds_dwordx4 v[220:221], off
	v_lshl_add_u64 v[222:223], s[30:31], 0, v[132:133]
	s_mov_b32 m0, s80
	s_nop 0
	global_load_lds_dwordx4 v[222:223], off
	s_barrier
	s_waitcnt lgkmcnt(0)
	s_setprio 1
	s_waitcnt lgkmcnt(0)
	v_mfma_f32_16x16x32_bf16 v[62:65], v[148:151], v[168:171], 0
	v_mfma_f32_16x16x32_bf16 v[58:61], v[156:159], v[168:171], 0
	v_mfma_f32_16x16x32_bf16 v[46:49], v[148:151], v[180:183], 0
	v_mfma_f32_16x16x32_bf16 v[42:45], v[156:159], v[180:183], 0
	v_mfma_f32_16x16x32_bf16 v[30:33], v[148:151], v[188:191], 0
	v_mfma_f32_16x16x32_bf16 v[26:29], v[156:159], v[188:191], 0
	v_mfma_f32_16x16x32_bf16 v[14:17], v[148:151], v[196:199], 0
	v_mfma_f32_16x16x32_bf16 v[10:13], v[156:159], v[196:199], 0
	v_mfma_f32_16x16x32_bf16 v[62:65], v[152:155], v[176:179], v[62:65]
	v_mfma_f32_16x16x32_bf16 v[58:61], v[160:163], v[176:179], v[58:61]
	v_mfma_f32_16x16x32_bf16 v[46:49], v[152:155], v[184:187], v[46:49]
	v_mfma_f32_16x16x32_bf16 v[42:45], v[160:163], v[184:187], v[42:45]
	v_mfma_f32_16x16x32_bf16 v[30:33], v[152:155], v[192:195], v[30:33]
	v_mfma_f32_16x16x32_bf16 v[26:29], v[160:163], v[192:195], v[26:29]
	v_mfma_f32_16x16x32_bf16 v[14:17], v[152:155], v[200:203], v[14:17]
	v_mfma_f32_16x16x32_bf16 v[10:13], v[160:163], v[200:203], v[10:13]
	s_setprio 0
	s_barrier
; #define PG8_STAGE(bufoff, gbase, voff) do { _Pragma("unroll") for (int _i = 0; _i < 2; ++_i) \
;         __builtin_amdgcn_global_load_lds((const unsigned*)((const char*)(gbase) + (voff)[_i]), (LAS unsigned*)(lds + (bufoff) + ldsw + _i * 8192), 16, 0, 0); } while (0)
; #define PG8_LDA(dst, b, h) do { _Pragma("unroll") for (int m = 0; m < 4; ++m) _Pragma("unroll") for (int k = 0; k < 2; ++k) dst[m][k] = *(const LAS bf16x8*)(lds + PG8_SA(b, h) + aoff + m * 2048 + k * 1024); } while (0)
; #define PG8_LDB(dst, b, h) do { _Pragma("unroll") for (int n = 0; n < 2; ++n) _Pragma("unroll") for (int k = 0; k < 2; ++k) dst[n][k] = *(const LAS bf16x8*)(lds + PG8_SB(b, h) + boff + n * 2048 + k * 1024); } while (0)
; #define PG8_MMA(ai, bj, At, Bt) do { __builtin_amdgcn_s_setprio(1); _Pragma("unroll") for (int m = 0; m < 4; ++m) _Pragma("unroll") for (int n = 0; n < 2; ++n) _Pragma("unroll") for (int k = 0; k < 2; ++k) \
;         acc[ai][bj][m][n] = __builtin_amdgcn_mfma_f32_16x16x32_bf16(Bt[n][k], At[m][k], acc[ai][bj][m][n], 0, 0, 0); __builtin_amdgcn_s_setprio(0); } while (0)
; #define PG8_WAIT_V(n) asm volatile("s_waitcnt vmcnt(" #n ")" ::: "memory")
; #define PG8_WAIT_L(n) asm volatile("s_waitcnt lgkmcnt(" #n ")" ::: "memory")
; #define PG8_BAR __builtin_amdgcn_s_barrier()
; #define PG8_SCHED __builtin_amdgcn_sched_barrier(0)
; template <class Epi>
; DI void gemm_phase(int wv, LAS unsigned char* lds, const GemmD g, const Epi& E) {
;     ...
;             PG8_STAGE(PG8_SB(0, 1), b2 + hstepB, voffB);
;             PG8_WAIT_V(6); PG8_BAR; PG8_MMA(1, 1, At, B1); PG8_BAR;
;             PG8_LDB(B0, 1, 0); PG8_SCHED; PG8_LDA(At, 1, 0); PG8_STAGE(PG8_SA(0, 1), a2 + hstepA, voffA);
;             PG8_WAIT_L(8); PG8_BAR; PG8_WAIT_L(0); PG8_MMA(0, 0, At, B0); PG8_BAR; PG8_SCHED;
;             PG8_LDB(B1, 1, 1); PG8_STAGE(PG8_SB(1, 0), b3, voffB);
	s_add_u32 s18, s28, 0x40000
	s_addc_u32 s19, s29, 0
	s_add_i32 s2, s2, s79
	v_lshl_add_u64 v[148:149], s[18:19], 0, v[0:1]
	s_mov_b32 m0, s2
	s_nop 0
	global_load_lds_dwordx4 v[148:149], off
	v_lshl_add_u64 v[148:149], s[18:19], 0, v[134:135]
	s_add_i32 m0, s2, 0x2000
	s_nop 0
	global_load_lds_dwordx4 v[148:149], off
	s_waitcnt vmcnt(6)
	s_barrier
	s_setprio 1
	v_mfma_f32_16x16x32_bf16 v[54:57], v[204:207], v[168:171], 0
	v_mfma_f32_16x16x32_bf16 v[50:53], v[212:215], v[168:171], 0
	v_mfma_f32_16x16x32_bf16 v[38:41], v[204:207], v[180:183], 0
	v_mfma_f32_16x16x32_bf16 v[34:37], v[212:215], v[180:183], 0
	v_mfma_f32_16x16x32_bf16 v[22:25], v[204:207], v[188:191], 0
	v_mfma_f32_16x16x32_bf16 v[18:21], v[212:215], v[188:191], 0
	v_mfma_f32_16x16x32_bf16 v[6:9], v[204:207], v[196:199], 0
	v_mfma_f32_16x16x32_bf16 v[2:5], v[212:215], v[196:199], 0
	v_mfma_f32_16x16x32_bf16 v[54:57], v[208:211], v[176:179], v[54:57]
	v_mfma_f32_16x16x32_bf16 v[50:53], v[216:219], v[176:179], v[50:53]
	v_mfma_f32_16x16x32_bf16 v[38:41], v[208:211], v[184:187], v[38:41]
	v_mfma_f32_16x16x32_bf16 v[34:37], v[216:219], v[184:187], v[34:37]
	v_mfma_f32_16x16x32_bf16 v[22:25], v[208:211], v[192:195], v[22:25]
	v_mfma_f32_16x16x32_bf16 v[18:21], v[216:219], v[192:195], v[18:21]
	v_mfma_f32_16x16x32_bf16 v[6:9], v[208:211], v[200:203], v[6:9]
	v_mfma_f32_16x16x32_bf16 v[2:5], v[216:219], v[200:203], v[2:5]
	s_setprio 0
	s_add_i32 s2, 0, 0x18000
	v_add_u32_e32 v147, s2, v144
	s_barrier
	ds_read_b128 v[148:151], v147
	ds_read_b128 v[152:155], v147 offset:1024
	ds_read_b128 v[156:159], v147 offset:2048
	ds_read_b128 v[160:163], v147 offset:3072
	s_add_u32 s18, s30, 0x40000
	s_addc_u32 s19, s31, 0
	s_mov_b32 m0, s81
	v_lshl_add_u64 v[204:205], s[18:19], 0, v[130:131]
	ds_read_b128 v[168:171], v146 offset:32768
	ds_read_b128 v[176:179], v146 offset:33792
	ds_read_b128 v[180:183], v146 offset:34816
	ds_read_b128 v[184:187], v146 offset:35840
	ds_read_b128 v[188:191], v146 offset:36864
	ds_read_b128 v[192:195], v146 offset:37888
	ds_read_b128 v[196:199], v146 offset:38912
	ds_read_b128 v[200:203], v146 offset:39936
	global_load_lds_dwordx4 v[204:205], off
	v_lshl_add_u64 v[204:205], s[18:19], 0, v[132:133]
	s_mov_b32 m0, s82
	s_nop 0
	global_load_lds_dwordx4 v[204:205], off
	s_waitcnt lgkmcnt(8)
	s_barrier
	s_waitcnt lgkmcnt(0)
	s_setprio 1
	s_waitcnt lgkmcnt(0)
	v_mfma_f32_16x16x32_bf16 v[126:129], v[148:151], v[168:171], v[126:129]
	v_mfma_f32_16x16x32_bf16 v[122:125], v[156:159], v[168:171], v[122:125]
	v_mfma_f32_16x16x32_bf16 v[110:113], v[148:151], v[180:183], v[110:113]
	v_mfma_f32_16x16x32_bf16 v[106:109], v[156:159], v[180:183], v[106:109]
	v_mfma_f32_16x16x32_bf16 v[94:97], v[148:151], v[188:191], v[94:97]
	v_mfma_f32_16x16x32_bf16 v[90:93], v[156:159], v[188:191], v[90:93]
	v_mfma_f32_16x16x32_bf16 v[78:81], v[148:151], v[196:199], v[78:81]
	v_mfma_f32_16x16x32_bf16 v[74:77], v[156:159], v[196:199], v[74:77]
	v_mfma_f32_16x16x32_bf16 v[126:129], v[152:155], v[176:179], v[126:129]
	v_mfma_f32_16x16x32_bf16 v[122:125], v[160:163], v[176:179], v[122:125]
	v_mfma_f32_16x16x32_bf16 v[110:113], v[152:155], v[184:187], v[110:113]
	v_mfma_f32_16x16x32_bf16 v[106:109], v[160:163], v[184:187], v[106:109]
	v_mfma_f32_16x16x32_bf16 v[94:97], v[152:155], v[192:195], v[94:97]
	v_mfma_f32_16x16x32_bf16 v[90:93], v[160:163], v[192:195], v[90:93]
	v_mfma_f32_16x16x32_bf16 v[78:81], v[152:155], v[200:203], v[78:81]
	v_mfma_f32_16x16x32_bf16 v[74:77], v[160:163], v[200:203], v[74:77]
	s_setprio 0
	s_barrier
	s_add_i32 s3, 0, 0x1c000
	s_add_i32 s2, s2, s79
	v_add_u32_e32 v147, s3, v144
	v_lshl_add_u64 v[140:141], v[140:141], 0, s[58:59]
	s_mov_b32 m0, s2
	ds_read_b128 v[204:207], v147
	ds_read_b128 v[208:211], v147 offset:1024
	ds_read_b128 v[212:215], v147 offset:2048
	ds_read_b128 v[216:219], v147 offset:3072
	global_load_lds_dwordx4 v[140:141], off
	v_lshl_add_u64 v[140:141], v[164:165], 0, s[58:59]
	s_add_i32 m0, s2, 0x2000
	s_nop 0
	global_load_lds_dwordx4 v[140:141], off
	s_barrier
; #define PG8_STAGE(bufoff, gbase, voff) do { _Pragma("unroll") for (int _i = 0; _i < 2; ++_i) \
;         __builtin_amdgcn_global_load_lds((const unsigned*)((const char*)(gbase) + (voff)[_i]), (LAS unsigned*)(lds + (bufoff) + ldsw + _i * 8192), 16, 0, 0); } while (0)
; #define PG8_LDA(dst, b, h) do { _Pragma("unroll") for (int m = 0; m < 4; ++m) _Pragma("unroll") for (int k = 0; k < 2; ++k) dst[m][k] = *(const LAS bf16x8*)(lds + PG8_SA(b, h) + aoff + m * 2048 + k * 1024); } while (0)
; #define PG8_MMA(ai, bj, At, Bt) do { __builtin_amdgcn_s_setprio(1); _Pragma("unroll") for (int m = 0; m < 4; ++m) _Pragma("unroll") for (int n = 0; n < 2; ++n) _Pragma("unroll") for (int k = 0; k < 2; ++k) \
;         acc[ai][bj][m][n] = __builtin_amdgcn_mfma_f32_16x16x32_bf16(Bt[n][k], At[m][k], acc[ai][bj][m][n], 0, 0, 0); __builtin_amdgcn_s_setprio(0); } while (0)
; #define PG8_WAIT_V(n) asm volatile("s_waitcnt vmcnt(" #n ")" ::: "memory")
; #define PG8_WAIT_L(n) asm volatile("s_waitcnt lgkmcnt(" #n ")" ::: "memory")
; #define PG8_BAR __builtin_amdgcn_s_barrier()
; #define PG8_SCHED __builtin_amdgcn_sched_barrier(0)
; template <class Epi>
; DI void gemm_phase(int wv, LAS unsigned char* lds, const GemmD g, const Epi& E) {
;     ...
;             PG8_BAR; PG8_WAIT_L(0); PG8_MMA(0, 1, At, B1); PG8_BAR;
;             PG8_LDA(At, 1, 1); PG8_STAGE(PG8_SA(1, 0), a3, voffA);
;             PG8_BAR; PG8_WAIT_L(0); PG8_MMA(1, 0, At, B0); PG8_BAR; PG8_SCHED;
;             PG8_STAGE(PG8_SB(1, 1), b3 + hstepB, voffB);
;             PG8_WAIT_V(6); PG8_BAR; PG8_MMA(1, 1, At, B1); PG8_BAR;
;         }
	s_waitcnt lgkmcnt(0)
	s_setprio 1
	s_waitcnt lgkmcnt(0)
	v_mfma_f32_16x16x32_bf16 v[118:121], v[204:207], v[168:171], v[118:121]
	v_mfma_f32_16x16x32_bf16 v[114:117], v[212:215], v[168:171], v[114:117]
	v_mfma_f32_16x16x32_bf16 v[102:105], v[204:207], v[180:183], v[102:105]
	v_mfma_f32_16x16x32_bf16 v[98:101], v[212:215], v[180:183], v[98:101]
	v_mfma_f32_16x16x32_bf16 v[86:89], v[204:207], v[188:191], v[86:89]
	v_mfma_f32_16x16x32_bf16 v[82:85], v[212:215], v[188:191], v[82:85]
	v_mfma_f32_16x16x32_bf16 v[70:73], v[204:207], v[196:199], v[70:73]
	v_mfma_f32_16x16x32_bf16 v[66:69], v[212:215], v[196:199], v[66:69]
	v_mfma_f32_16x16x32_bf16 v[118:121], v[208:211], v[176:179], v[118:121]
	v_mfma_f32_16x16x32_bf16 v[114:117], v[216:219], v[176:179], v[114:117]
	v_mfma_f32_16x16x32_bf16 v[102:105], v[208:211], v[184:187], v[102:105]
	v_mfma_f32_16x16x32_bf16 v[98:101], v[216:219], v[184:187], v[98:101]
	v_mfma_f32_16x16x32_bf16 v[86:89], v[208:211], v[192:195], v[86:89]
	v_mfma_f32_16x16x32_bf16 v[82:85], v[216:219], v[192:195], v[82:85]
	v_mfma_f32_16x16x32_bf16 v[70:73], v[208:211], v[200:203], v[70:73]
	v_mfma_f32_16x16x32_bf16 v[66:69], v[216:219], v[200:203], v[66:69]
	s_setprio 0
	s_mov_b32 m0, s83
	v_lshl_add_u64 v[140:141], v[220:221], 0, s[58:59]
	s_barrier
	ds_read_b128 v[168:171], v146 offset:49152
	ds_read_b128 v[176:179], v146 offset:50176
	ds_read_b128 v[180:183], v146 offset:51200
	ds_read_b128 v[184:187], v146 offset:52224
	ds_read_b128 v[188:191], v146 offset:53248
	ds_read_b128 v[192:195], v146 offset:54272
	ds_read_b128 v[196:199], v146 offset:55296
	ds_read_b128 v[200:203], v146 offset:56320
	global_load_lds_dwordx4 v[140:141], off
	v_lshl_add_u64 v[140:141], v[222:223], 0, s[58:59]
	s_mov_b32 m0, s84
	s_nop 0
	global_load_lds_dwordx4 v[140:141], off
	s_barrier
	s_waitcnt lgkmcnt(0)
	s_setprio 1
	s_waitcnt lgkmcnt(0)
	v_mfma_f32_16x16x32_bf16 v[62:65], v[148:151], v[168:171], v[62:65]
	v_mfma_f32_16x16x32_bf16 v[58:61], v[156:159], v[168:171], v[58:61]
	v_mfma_f32_16x16x32_bf16 v[46:49], v[148:151], v[180:183], v[46:49]
	v_mfma_f32_16x16x32_bf16 v[42:45], v[156:159], v[180:183], v[42:45]
	v_mfma_f32_16x16x32_bf16 v[30:33], v[148:151], v[188:191], v[30:33]
	v_mfma_f32_16x16x32_bf16 v[26:29], v[156:159], v[188:191], v[26:29]
	v_mfma_f32_16x16x32_bf16 v[14:17], v[148:151], v[196:199], v[14:17]
	v_mfma_f32_16x16x32_bf16 v[10:13], v[156:159], v[196:199], v[10:13]
	v_mfma_f32_16x16x32_bf16 v[62:65], v[152:155], v[176:179], v[62:65]
	v_mfma_f32_16x16x32_bf16 v[58:61], v[160:163], v[176:179], v[58:61]
	v_mfma_f32_16x16x32_bf16 v[46:49], v[152:155], v[184:187], v[46:49]
	v_mfma_f32_16x16x32_bf16 v[42:45], v[160:163], v[184:187], v[42:45]
	v_mfma_f32_16x16x32_bf16 v[30:33], v[152:155], v[192:195], v[30:33]
	v_mfma_f32_16x16x32_bf16 v[26:29], v[160:163], v[192:195], v[26:29]
	v_mfma_f32_16x16x32_bf16 v[14:17], v[152:155], v[200:203], v[14:17]
	v_mfma_f32_16x16x32_bf16 v[10:13], v[160:163], v[200:203], v[10:13]
	s_setprio 0
	s_barrier
	s_add_u32 s18, s28, 0x40080
	s_addc_u32 s19, s29, 0
	s_add_i32 s2, s3, s79
	v_lshl_add_u64 v[140:141], s[18:19], 0, v[0:1]
	s_mov_b32 m0, s2
	s_nop 0
	global_load_lds_dwordx4 v[140:141], off
	v_lshl_add_u64 v[140:141], s[18:19], 0, v[134:135]
	s_add_i32 m0, s2, 0x2000
	s_nop 0
	global_load_lds_dwordx4 v[140:141], off
	s_waitcnt vmcnt(6)
	s_barrier
	s_setprio 1
	v_mfma_f32_16x16x32_bf16 v[54:57], v[204:207], v[168:171], v[54:57]
	v_mfma_f32_16x16x32_bf16 v[50:53], v[212:215], v[168:171], v[50:53]
	v_mfma_f32_16x16x32_bf16 v[38:41], v[204:207], v[180:183], v[38:41]
	v_mfma_f32_16x16x32_bf16 v[34:37], v[212:215], v[180:183], v[34:37]
	v_mfma_f32_16x16x32_bf16 v[22:25], v[204:207], v[188:191], v[22:25]
	v_mfma_f32_16x16x32_bf16 v[18:21], v[212:215], v[188:191], v[18:21]
	v_mfma_f32_16x16x32_bf16 v[6:9], v[204:207], v[196:199], v[6:9]
	v_mfma_f32_16x16x32_bf16 v[2:5], v[212:215], v[196:199], v[2:5]
	v_mfma_f32_16x16x32_bf16 v[54:57], v[208:211], v[176:179], v[54:57]
	v_mfma_f32_16x16x32_bf16 v[50:53], v[216:219], v[176:179], v[50:53]
	v_mfma_f32_16x16x32_bf16 v[38:41], v[208:211], v[184:187], v[38:41]
	v_mfma_f32_16x16x32_bf16 v[34:37], v[216:219], v[184:187], v[34:37]
	v_mfma_f32_16x16x32_bf16 v[22:25], v[208:211], v[192:195], v[22:25]
	v_mfma_f32_16x16x32_bf16 v[18:21], v[216:219], v[192:195], v[18:21]
	v_mfma_f32_16x16x32_bf16 v[6:9], v[208:211], v[200:203], v[6:9]
	v_mfma_f32_16x16x32_bf16 v[2:5], v[216:219], v[200:203], v[2:5]
	s_setprio 0
	s_add_i32 s41, s41, 2
	s_add_u32 s26, s26, 0x100
	s_addc_u32 s27, s27, 0
	s_add_u32 s36, s36, 0x100
	s_addc_u32 s38, s38, 0
	s_cmp_gt_u32 s41, 13
	s_barrier
	s_cbranch_scc0 .LBB0_490
	s_branch .Lgemm_epi_b

; DI unsigned pk2(float lo, float hi) { f32x2 f = {lo, hi}; bf2_t v = __builtin_convertvector(f, bf2_t); return __builtin_bit_cast(unsigned, v); }
;     DI void operator()(const f32x4 (&acc)[2][2][4][2], const Unit& u, int wr, int wc, int fr, int fq) const {
;         const int row0 = u.pm * BM + wr * 64 + fr; const int col0 = u.pn * BM + wc * 32 + 8 * fq;
; #pragma unroll
;         for (int ai = 0; ai < 2; ++ai)
; #pragma unroll
;             for (int m = 0; m < 4; ++m) { bf16_t* rowp = O + (size_t)(row0 + ai * HALF + m * 16) * ldc + col0;
; #pragma unroll
;                 for (int bj = 0; bj < 2; ++bj) { f32x4 v0 = acc[ai][bj][m][0], v1 = acc[ai][bj][m][1];
;                     if (ACT == 1) {
; #pragma unroll
;                         for (int j = 0; j < 4; ++j) { float a = fmaxf(v0[j], 0.f), b = fmaxf(v1[j], 0.f); v0[j] = a * a; v1[j] = b * b; } }
;                     u32x4 w; w.x = pk2(v0[0], v0[1]); w.y = pk2(v0[2], v0[3]); w.z = pk2(v1[0], v1[1]); w.w = pk2(v1[2], v1[3]);
;                     *(u32x4*)(rowp + bj * HALF) = w; } }
.Lgemm_epi_b:
	v_lshl_add_u32 v148, s24, 8, v143
	v_lshl_or_b32 v140, s12, 8, v145
	v_ashrrev_i32_e32 v149, 31, v148
	v_ashrrev_i32_e32 v141, 31, v140
	v_lshlrev_b64 v[150:151], 13, v[148:149]
	v_max_f32_e32 v122, v122, v122
	v_max_f32_e32 v123, v123, v123
	v_lshl_add_u64 v[150:151], s[10:11], 0, v[150:151]
	v_lshlrev_b64 v[152:153], 1, v[140:141]
	v_max_f32_e32 v122, 0, v122
	v_max_f32_e32 v123, 0, v123
	v_lshl_add_u64 v[140:141], v[150:151], 0, v[152:153]
	v_pk_mul_f32 v[150:151], v[122:123], v[122:123]
	v_max_f32_e32 v123, v124, v124
	v_max_f32_e32 v126, v126, v126
	v_max_f32_e32 v127, v127, v127
	v_max_f32_e32 v122, v128, v128
	v_max_f32_e32 v124, 0, v123
	v_max_f32_e32 v123, v129, v129
	v_max_f32_e32 v125, v125, v125
	v_max_f32_e32 v126, 0, v126
	v_max_f32_e32 v127, 0, v127
	v_max_f32_e32 v122, 0, v122
	v_max_f32_e32 v123, 0, v123
	v_max_f32_e32 v125, 0, v125
	v_pk_mul_f32 v[126:127], v[126:127], v[126:127]
	v_pk_mul_f32 v[128:129], v[122:123], v[122:123]
	v_pk_mul_f32 v[154:155], v[124:125], v[124:125]
	v_max_f32_e32 v114, v114, v114
	v_max_f32_e32 v115, v115, v115
	v_cvt_pk_bf16_f32 v122, v126, v127
	v_cvt_pk_bf16_f32 v123, v128, v129
	v_cvt_pk_bf16_f32 v124, v150, v151
	v_cvt_pk_bf16_f32 v125, v154, v155
	v_max_f32_e32 v114, 0, v114
	v_max_f32_e32 v115, 0, v115
	global_store_dwordx4 v[140:141], v[122:125], off
	v_max_f32_e32 v118, v118, v118
	v_max_f32_e32 v119, v119, v119
	v_pk_mul_f32 v[122:123], v[114:115], v[114:115]
	v_max_f32_e32 v115, v116, v116
	v_max_f32_e32 v114, v120, v120
	v_max_f32_e32 v116, 0, v115
	v_max_f32_e32 v115, v121, v121
	v_max_f32_e32 v117, v117, v117
	v_max_f32_e32 v118, 0, v118
	v_max_f32_e32 v119, 0, v119
	v_max_f32_e32 v114, 0, v114
	v_max_f32_e32 v115, 0, v115
	v_max_f32_e32 v117, 0, v117
	v_pk_mul_f32 v[118:119], v[118:119], v[118:119]
	v_pk_mul_f32 v[120:121], v[114:115], v[114:115]
	v_pk_mul_f32 v[124:125], v[116:117], v[116:117]
	v_max_f32_e32 v106, v106, v106
	v_max_f32_e32 v107, v107, v107
	v_cvt_pk_bf16_f32 v114, v118, v119
	v_cvt_pk_bf16_f32 v115, v120, v121
	v_cvt_pk_bf16_f32 v116, v122, v123
	v_cvt_pk_bf16_f32 v117, v124, v125
	v_max_f32_e32 v106, 0, v106
	v_max_f32_e32 v107, 0, v107
	global_store_dwordx4 v[140:141], v[114:117], off offset:256
	v_max_f32_e32 v110, v110, v110
	v_max_f32_e32 v111, v111, v111
	v_or_b32_e32 v114, 16, v148
	v_pk_mul_f32 v[116:117], v[106:107], v[106:107]
	v_max_f32_e32 v107, v108, v108
	v_ashrrev_i32_e32 v115, 31, v114
	v_max_f32_e32 v106, v112, v112
	v_max_f32_e32 v108, 0, v107
	v_max_f32_e32 v107, v113, v113
	v_max_f32_e32 v109, v109, v109
	v_lshlrev_b64 v[114:115], 13, v[114:115]
	v_max_f32_e32 v110, 0, v110
	v_max_f32_e32 v111, 0, v111
	v_max_f32_e32 v106, 0, v106
	v_max_f32_e32 v107, 0, v107
	v_max_f32_e32 v109, 0, v109
	v_lshl_add_u64 v[114:115], s[10:11], 0, v[114:115]
	v_pk_mul_f32 v[110:111], v[110:111], v[110:111]
	v_pk_mul_f32 v[112:113], v[106:107], v[106:107]
	v_pk_mul_f32 v[118:119], v[108:109], v[108:109]
	v_max_f32_e32 v98, v98, v98
	v_max_f32_e32 v99, v99, v99
	v_lshl_add_u64 v[114:115], v[114:115], 0, v[152:153]
	v_cvt_pk_bf16_f32 v106, v110, v111
	v_cvt_pk_bf16_f32 v107, v112, v113
	v_cvt_pk_bf16_f32 v108, v116, v117
	v_cvt_pk_bf16_f32 v109, v118, v119
	v_max_f32_e32 v98, 0, v98
	v_max_f32_e32 v99, 0, v99
	global_store_dwordx4 v[114:115], v[106:109], off
	v_max_f32_e32 v102, v102, v102
	v_max_f32_e32 v103, v103, v103
	v_pk_mul_f32 v[106:107], v[98:99], v[98:99]
	v_max_f32_e32 v99, v100, v100
	v_max_f32_e32 v98, v104, v104
	v_max_f32_e32 v100, 0, v99
	v_max_f32_e32 v99, v105, v105
	v_max_f32_e32 v101, v101, v101
	v_max_f32_e32 v102, 0, v102
	v_max_f32_e32 v103, 0, v103
	v_max_f32_e32 v98, 0, v98
	v_max_f32_e32 v99, 0, v99
	v_max_f32_e32 v101, 0, v101
	v_pk_mul_f32 v[102:103], v[102:103], v[102:103]
	v_pk_mul_f32 v[104:105], v[98:99], v[98:99]
	v_pk_mul_f32 v[108:109], v[100:101], v[100:101]
	v_max_f32_e32 v90, v90, v90
	v_max_f32_e32 v91, v91, v91
	v_cvt_pk_bf16_f32 v98, v102, v103
	v_cvt_pk_bf16_f32 v99, v104, v105
	v_cvt_pk_bf16_f32 v100, v106, v107
	v_cvt_pk_bf16_f32 v101, v108, v109
	v_max_f32_e32 v90, 0, v90
	v_max_f32_e32 v91, 0, v91
	global_store_dwordx4 v[114:115], v[98:101], off offset:256
	v_max_f32_e32 v94, v94, v94
	v_max_f32_e32 v95, v95, v95
	v_or_b32_e32 v98, 32, v148
	v_pk_mul_f32 v[100:101], v[90:91], v[90:91]
	v_max_f32_e32 v91, v92, v92
	v_ashrrev_i32_e32 v99, 31, v98
	v_max_f32_e32 v90, v96, v96
	v_max_f32_e32 v92, 0, v91
	v_max_f32_e32 v91, v97, v97
	v_max_f32_e32 v93, v93, v93
	v_lshlrev_b64 v[98:99], 13, v[98:99]
	v_max_f32_e32 v94, 0, v94
	v_max_f32_e32 v95, 0, v95
	v_max_f32_e32 v90, 0, v90
	v_max_f32_e32 v91, 0, v91
	v_max_f32_e32 v93, 0, v93
	v_lshl_add_u64 v[98:99], s[10:11], 0, v[98:99]
	v_pk_mul_f32 v[94:95], v[94:95], v[94:95]
	v_pk_mul_f32 v[96:97], v[90:91], v[90:91]
	v_pk_mul_f32 v[102:103], v[92:93], v[92:93]
	v_max_f32_e32 v82, v82, v82
	v_max_f32_e32 v83, v83, v83
	v_lshl_add_u64 v[98:99], v[98:99], 0, v[152:153]
	v_cvt_pk_bf16_f32 v90, v94, v95
	v_cvt_pk_bf16_f32 v91, v96, v97
	v_cvt_pk_bf16_f32 v92, v100, v101
	v_cvt_pk_bf16_f32 v93, v102, v103
	v_max_f32_e32 v82, 0, v82
	v_max_f32_e32 v83, 0, v83
	global_store_dwordx4 v[98:99], v[90:93], off
	v_max_f32_e32 v86, v86, v86
	v_max_f32_e32 v87, v87, v87
	v_pk_mul_f32 v[90:91], v[82:83], v[82:83]
	v_max_f32_e32 v83, v84, v84
	v_max_f32_e32 v82, v88, v88
	v_max_f32_e32 v84, 0, v83
	v_max_f32_e32 v83, v89, v89
	v_max_f32_e32 v85, v85, v85
	v_max_f32_e32 v86, 0, v86
	v_max_f32_e32 v87, 0, v87
	v_max_f32_e32 v82, 0, v82
	v_max_f32_e32 v83, 0, v83
	v_max_f32_e32 v85, 0, v85
	v_pk_mul_f32 v[86:87], v[86:87], v[86:87]
	v_pk_mul_f32 v[88:89], v[82:83], v[82:83]
; DI unsigned pk2(float lo, float hi) { f32x2 f = {lo, hi}; bf2_t v = __builtin_convertvector(f, bf2_t); return __builtin_bit_cast(unsigned, v); }
;     DI void operator()(const f32x4 (&acc)[2][2][4][2], const Unit& u, int wr, int wc, int fr, int fq) const {
;     ...
;             for (int m = 0; m < 4; ++m) { bf16_t* rowp = O + (size_t)(row0 + ai * HALF + m * 16) * ldc + col0;
; #pragma unroll
;                 for (int bj = 0; bj < 2; ++bj) { f32x4 v0 = acc[ai][bj][m][0], v1 = acc[ai][bj][m][1];
;                     if (ACT == 1) {
; #pragma unroll
;                         for (int j = 0; j < 4; ++j) { float a = fmaxf(v0[j], 0.f), b = fmaxf(v1[j], 0.f); v0[j] = a * a; v1[j] = b * b; } }
;                     u32x4 w; w.x = pk2(v0[0], v0[1]); w.y = pk2(v0[2], v0[3]); w.z = pk2(v1[0], v1[1]); w.w = pk2(v1[2], v1[3]);
;                     *(u32x4*)(rowp + bj * HALF) = w; } }
	v_pk_mul_f32 v[92:93], v[84:85], v[84:85]
	v_max_f32_e32 v74, v74, v74
	v_max_f32_e32 v75, v75, v75
	v_cvt_pk_bf16_f32 v82, v86, v87
	v_cvt_pk_bf16_f32 v83, v88, v89
	v_cvt_pk_bf16_f32 v84, v90, v91
	v_cvt_pk_bf16_f32 v85, v92, v93
	v_max_f32_e32 v74, 0, v74
	v_max_f32_e32 v75, 0, v75
	global_store_dwordx4 v[98:99], v[82:85], off offset:256
	v_max_f32_e32 v78, v78, v78
	v_max_f32_e32 v79, v79, v79
	v_or_b32_e32 v82, 48, v148
	v_pk_mul_f32 v[84:85], v[74:75], v[74:75]
	v_max_f32_e32 v75, v76, v76
	v_ashrrev_i32_e32 v83, 31, v82
	v_max_f32_e32 v74, v80, v80
	v_max_f32_e32 v76, 0, v75
	v_max_f32_e32 v75, v81, v81
	v_max_f32_e32 v77, v77, v77
	v_lshlrev_b64 v[82:83], 13, v[82:83]
	v_max_f32_e32 v78, 0, v78
	v_max_f32_e32 v79, 0, v79
	v_max_f32_e32 v74, 0, v74
	v_max_f32_e32 v75, 0, v75
	v_max_f32_e32 v77, 0, v77
	v_lshl_add_u64 v[82:83], s[10:11], 0, v[82:83]
	v_pk_mul_f32 v[78:79], v[78:79], v[78:79]
	v_pk_mul_f32 v[80:81], v[74:75], v[74:75]
	v_pk_mul_f32 v[86:87], v[76:77], v[76:77]
	v_max_f32_e32 v66, v66, v66
	v_max_f32_e32 v67, v67, v67
	v_lshl_add_u64 v[82:83], v[82:83], 0, v[152:153]
	v_cvt_pk_bf16_f32 v74, v78, v79
	v_cvt_pk_bf16_f32 v75, v80, v81
	v_cvt_pk_bf16_f32 v76, v84, v85
	v_cvt_pk_bf16_f32 v77, v86, v87
	v_max_f32_e32 v66, 0, v66
	v_max_f32_e32 v67, 0, v67
	global_store_dwordx4 v[82:83], v[74:77], off
	v_max_f32_e32 v70, v70, v70
	v_max_f32_e32 v71, v71, v71
	v_pk_mul_f32 v[74:75], v[66:67], v[66:67]
	v_max_f32_e32 v67, v68, v68
	v_max_f32_e32 v66, v72, v72
	v_max_f32_e32 v68, 0, v67
	v_max_f32_e32 v67, v73, v73
	v_max_f32_e32 v69, v69, v69
	v_max_f32_e32 v70, 0, v70
	v_max_f32_e32 v71, 0, v71
	v_max_f32_e32 v66, 0, v66
	v_max_f32_e32 v67, 0, v67
	v_max_f32_e32 v69, 0, v69
	v_pk_mul_f32 v[70:71], v[70:71], v[70:71]
	v_pk_mul_f32 v[72:73], v[66:67], v[66:67]
	v_pk_mul_f32 v[76:77], v[68:69], v[68:69]
	v_max_f32_e32 v58, v58, v58
	v_max_f32_e32 v59, v59, v59
	v_cvt_pk_bf16_f32 v66, v70, v71
	v_cvt_pk_bf16_f32 v67, v72, v73
	v_cvt_pk_bf16_f32 v68, v74, v75
	v_cvt_pk_bf16_f32 v69, v76, v77
	v_max_f32_e32 v58, 0, v58
	v_max_f32_e32 v59, 0, v59
	global_store_dwordx4 v[82:83], v[66:69], off offset:256
	v_max_f32_e32 v62, v62, v62
	v_max_f32_e32 v63, v63, v63
	v_pk_mul_f32 v[68:69], v[58:59], v[58:59]
	v_max_f32_e32 v59, v60, v60
	v_max_f32_e32 v62, 0, v62
	v_max_f32_e32 v63, 0, v63
	v_max_f32_e32 v58, v64, v64
	v_max_f32_e32 v60, 0, v59
	v_max_f32_e32 v59, v65, v65
	v_max_f32_e32 v61, v61, v61
	v_pk_mul_f32 v[62:63], v[62:63], v[62:63]
	v_max_f32_e32 v58, 0, v58
	v_max_f32_e32 v59, 0, v59
	v_max_f32_e32 v61, 0, v61
	v_pk_mul_f32 v[64:65], v[58:59], v[58:59]
	v_pk_mul_f32 v[70:71], v[60:61], v[60:61]
	v_cvt_pk_bf16_f32 v58, v62, v63
	v_add_co_u32_e32 v62, vcc, s74, v140
	v_max_f32_e32 v50, v50, v50
	v_max_f32_e32 v51, v51, v51
	v_cvt_pk_bf16_f32 v59, v64, v65
	v_cvt_pk_bf16_f32 v60, v68, v69
	v_cvt_pk_bf16_f32 v61, v70, v71
	v_addc_co_u32_e32 v63, vcc, 0, v141, vcc
	v_max_f32_e32 v50, 0, v50
	v_max_f32_e32 v51, 0, v51
	global_store_dwordx4 v[62:63], v[58:61], off
	v_max_f32_e32 v54, v54, v54
	v_max_f32_e32 v55, v55, v55
	v_pk_mul_f32 v[58:59], v[50:51], v[50:51]
	v_max_f32_e32 v51, v52, v52
	v_max_f32_e32 v50, v56, v56
	v_max_f32_e32 v52, 0, v51
	v_max_f32_e32 v51, v57, v57
	v_max_f32_e32 v53, v53, v53
	v_max_f32_e32 v54, 0, v54
	v_max_f32_e32 v55, 0, v55
	v_max_f32_e32 v50, 0, v50
	v_max_f32_e32 v51, 0, v51
	v_max_f32_e32 v53, 0, v53
	s_mov_b64 s[12:13], 0x100000
	v_pk_mul_f32 v[54:55], v[54:55], v[54:55]
	v_pk_mul_f32 v[56:57], v[50:51], v[50:51]
	v_pk_mul_f32 v[60:61], v[52:53], v[52:53]
	v_max_f32_e32 v42, v42, v42
	v_max_f32_e32 v43, v43, v43
	v_lshl_add_u64 v[66:67], v[140:141], 0, s[12:13]
	v_cvt_pk_bf16_f32 v50, v54, v55
	v_cvt_pk_bf16_f32 v51, v56, v57
	v_cvt_pk_bf16_f32 v52, v58, v59
	v_cvt_pk_bf16_f32 v53, v60, v61
	v_max_f32_e32 v42, 0, v42
	v_max_f32_e32 v43, 0, v43
	global_store_dwordx4 v[66:67], v[50:53], off offset:256
	v_max_f32_e32 v46, v46, v46
	v_max_f32_e32 v47, v47, v47
	v_pk_mul_f32 v[52:53], v[42:43], v[42:43]
	v_max_f32_e32 v43, v44, v44
	v_max_f32_e32 v46, 0, v46
	v_max_f32_e32 v47, 0, v47
	v_max_f32_e32 v42, v48, v48
	v_max_f32_e32 v44, 0, v43
	v_max_f32_e32 v43, v49, v49
	v_max_f32_e32 v45, v45, v45
	v_pk_mul_f32 v[46:47], v[46:47], v[46:47]
	v_max_f32_e32 v42, 0, v42
	v_max_f32_e32 v43, 0, v43
	v_max_f32_e32 v45, 0, v45
	s_mov_b32 s2, 0x120000
	v_pk_mul_f32 v[48:49], v[42:43], v[42:43]
	v_pk_mul_f32 v[54:55], v[44:45], v[44:45]
	v_cvt_pk_bf16_f32 v42, v46, v47
	v_add_co_u32_e32 v46, vcc, s2, v140
	v_max_f32_e32 v34, v34, v34
	v_max_f32_e32 v35, v35, v35
	v_cvt_pk_bf16_f32 v43, v48, v49
	v_cvt_pk_bf16_f32 v44, v52, v53
	v_cvt_pk_bf16_f32 v45, v54, v55
; DI unsigned pk2(float lo, float hi) { f32x2 f = {lo, hi}; bf2_t v = __builtin_convertvector(f, bf2_t); return __builtin_bit_cast(unsigned, v); }
; #define PG8_WAIT_V(n) asm volatile("s_waitcnt vmcnt(" #n ")" ::: "memory")
; #define PG8_BAR __builtin_amdgcn_s_barrier()
;     DI void operator()(const f32x4 (&acc)[2][2][4][2], const Unit& u, int wr, int wc, int fr, int fq) const {
;     ...
;                 for (int bj = 0; bj < 2; ++bj) { f32x4 v0 = acc[ai][bj][m][0], v1 = acc[ai][bj][m][1];
;                     if (ACT == 1) {
; #pragma unroll
;                         for (int j = 0; j < 4; ++j) { float a = fmaxf(v0[j], 0.f), b = fmaxf(v1[j], 0.f); v0[j] = a * a; v1[j] = b * b; } }
;                     u32x4 w; w.x = pk2(v0[0], v0[1]); w.y = pk2(v0[2], v0[3]); w.z = pk2(v1[0], v1[1]); w.w = pk2(v1[2], v1[3]);
;                     *(u32x4*)(rowp + bj * HALF) = w; } }
; template <class Epi>
; DI void gemm_phase(int wv, LAS unsigned char* lds, const GemmD g, const Epi& E) {
;     ...
;         E(acc, cur, wr, wc, fr, fq);
;         if (!has_next) break;
; #pragma unroll
;         for (int a = 0; a < 2; ++a)
; #pragma unroll
;             for (int b = 0; b < 2; ++b)
; #pragma unroll
;                 for (int m = 0; m < 4; ++m)
; #pragma unroll
;                     for (int n = 0; n < 2; ++n) acc[a][b][m][n] = (f32x4){0.f, 0.f, 0.f, 0.f};
;         cur = nxt; cA = nA; cB = nB; ++ui;
;     }
;     PG8_WAIT_V(0);
;     if (wr == 0) PG8_BAR;
;     PG8_BAR;
	v_addc_co_u32_e32 v47, vcc, 0, v141, vcc
	v_max_f32_e32 v34, 0, v34
	v_max_f32_e32 v35, 0, v35
	global_store_dwordx4 v[46:47], v[42:45], off
	v_max_f32_e32 v38, v38, v38
	v_max_f32_e32 v39, v39, v39
	v_pk_mul_f32 v[42:43], v[34:35], v[34:35]
	v_max_f32_e32 v35, v36, v36
	v_max_f32_e32 v34, v40, v40
	v_max_f32_e32 v36, 0, v35
	v_max_f32_e32 v35, v41, v41
	v_max_f32_e32 v37, v37, v37
	v_max_f32_e32 v38, 0, v38
	v_max_f32_e32 v39, 0, v39
	v_max_f32_e32 v34, 0, v34
	v_max_f32_e32 v35, 0, v35
	v_max_f32_e32 v37, 0, v37
	s_mov_b64 s[12:13], 0x120000
	v_pk_mul_f32 v[38:39], v[38:39], v[38:39]
	v_pk_mul_f32 v[40:41], v[34:35], v[34:35]
	v_pk_mul_f32 v[44:45], v[36:37], v[36:37]
	v_max_f32_e32 v26, v26, v26
	v_max_f32_e32 v27, v27, v27
	v_lshl_add_u64 v[50:51], v[140:141], 0, s[12:13]
	v_cvt_pk_bf16_f32 v34, v38, v39
	v_cvt_pk_bf16_f32 v35, v40, v41
	v_cvt_pk_bf16_f32 v36, v42, v43
	v_cvt_pk_bf16_f32 v37, v44, v45
	v_max_f32_e32 v26, 0, v26
	v_max_f32_e32 v27, 0, v27
	global_store_dwordx4 v[50:51], v[34:37], off offset:256
	v_max_f32_e32 v30, v30, v30
	v_max_f32_e32 v31, v31, v31
	v_pk_mul_f32 v[36:37], v[26:27], v[26:27]
	v_max_f32_e32 v27, v28, v28
	v_max_f32_e32 v30, 0, v30
	v_max_f32_e32 v31, 0, v31
	v_max_f32_e32 v26, v32, v32
	v_max_f32_e32 v28, 0, v27
	v_max_f32_e32 v27, v33, v33
	v_max_f32_e32 v29, v29, v29
	v_pk_mul_f32 v[30:31], v[30:31], v[30:31]
	v_max_f32_e32 v26, 0, v26
	v_max_f32_e32 v27, 0, v27
	v_max_f32_e32 v29, 0, v29
	s_mov_b32 s2, 0x140000
	v_pk_mul_f32 v[32:33], v[26:27], v[26:27]
	v_pk_mul_f32 v[38:39], v[28:29], v[28:29]
	v_cvt_pk_bf16_f32 v26, v30, v31
	v_add_co_u32_e32 v30, vcc, s2, v140
	v_max_f32_e32 v18, v18, v18
	v_max_f32_e32 v19, v19, v19
	v_cvt_pk_bf16_f32 v27, v32, v33
	v_cvt_pk_bf16_f32 v28, v36, v37
	v_cvt_pk_bf16_f32 v29, v38, v39
	v_addc_co_u32_e32 v31, vcc, 0, v141, vcc
	v_max_f32_e32 v18, 0, v18
	v_max_f32_e32 v19, 0, v19
	global_store_dwordx4 v[30:31], v[26:29], off
	v_max_f32_e32 v22, v22, v22
	v_max_f32_e32 v23, v23, v23
	v_pk_mul_f32 v[26:27], v[18:19], v[18:19]
	v_max_f32_e32 v19, v20, v20
	v_max_f32_e32 v18, v24, v24
	v_max_f32_e32 v20, 0, v19
	v_max_f32_e32 v19, v25, v25
	v_max_f32_e32 v21, v21, v21
	v_max_f32_e32 v22, 0, v22
	v_max_f32_e32 v23, 0, v23
	v_max_f32_e32 v18, 0, v18
	v_max_f32_e32 v19, 0, v19
	v_max_f32_e32 v21, 0, v21
	s_mov_b64 s[12:13], 0x140000
	v_pk_mul_f32 v[22:23], v[22:23], v[22:23]
	v_pk_mul_f32 v[24:25], v[18:19], v[18:19]
	v_pk_mul_f32 v[28:29], v[20:21], v[20:21]
	v_max_f32_e32 v10, v10, v10
	v_max_f32_e32 v11, v11, v11
	v_lshl_add_u64 v[34:35], v[140:141], 0, s[12:13]
	v_cvt_pk_bf16_f32 v18, v22, v23
	v_cvt_pk_bf16_f32 v19, v24, v25
	v_cvt_pk_bf16_f32 v20, v26, v27
	v_cvt_pk_bf16_f32 v21, v28, v29
	v_max_f32_e32 v10, 0, v10
	v_max_f32_e32 v11, 0, v11
	global_store_dwordx4 v[34:35], v[18:21], off offset:256
	v_max_f32_e32 v14, v14, v14
	v_max_f32_e32 v15, v15, v15
	v_pk_mul_f32 v[20:21], v[10:11], v[10:11]
	v_max_f32_e32 v11, v12, v12
	v_max_f32_e32 v14, 0, v14
	v_max_f32_e32 v15, 0, v15
	v_max_f32_e32 v10, v16, v16
	v_max_f32_e32 v12, 0, v11
	v_max_f32_e32 v11, v17, v17
	v_max_f32_e32 v13, v13, v13
	v_pk_mul_f32 v[14:15], v[14:15], v[14:15]
	v_max_f32_e32 v10, 0, v10
	v_max_f32_e32 v11, 0, v11
	v_max_f32_e32 v13, 0, v13
	s_mov_b32 s2, 0x160000
	v_pk_mul_f32 v[16:17], v[10:11], v[10:11]
	v_pk_mul_f32 v[22:23], v[12:13], v[12:13]
	v_cvt_pk_bf16_f32 v10, v14, v15
	v_add_co_u32_e32 v14, vcc, s2, v140
	v_max_f32_e32 v2, v2, v2
	v_max_f32_e32 v3, v3, v3
	v_cvt_pk_bf16_f32 v11, v16, v17
	v_cvt_pk_bf16_f32 v12, v20, v21
	v_cvt_pk_bf16_f32 v13, v22, v23
	v_addc_co_u32_e32 v15, vcc, 0, v141, vcc
	v_max_f32_e32 v2, 0, v2
	v_max_f32_e32 v3, 0, v3
	global_store_dwordx4 v[14:15], v[10:13], off
	v_max_f32_e32 v6, v6, v6
	v_max_f32_e32 v7, v7, v7
	v_pk_mul_f32 v[10:11], v[2:3], v[2:3]
	v_max_f32_e32 v3, v4, v4
	v_max_f32_e32 v2, v8, v8
	v_max_f32_e32 v4, 0, v3
	v_max_f32_e32 v3, v9, v9
	v_max_f32_e32 v5, v5, v5
	v_max_f32_e32 v6, 0, v6
	v_max_f32_e32 v7, 0, v7
	v_max_f32_e32 v2, 0, v2
	v_max_f32_e32 v3, 0, v3
	v_max_f32_e32 v5, 0, v5
	s_mov_b64 s[12:13], 0x160000
	v_pk_mul_f32 v[6:7], v[6:7], v[6:7]
	v_pk_mul_f32 v[8:9], v[2:3], v[2:3]
	v_pk_mul_f32 v[12:13], v[4:5], v[4:5]
	v_lshl_add_u64 v[18:19], v[140:141], 0, s[12:13]
	v_cvt_pk_bf16_f32 v2, v6, v7
	v_cvt_pk_bf16_f32 v3, v8, v9
	v_cvt_pk_bf16_f32 v4, v10, v11
	v_cvt_pk_bf16_f32 v5, v12, v13
	s_and_b64 vcc, exec, s[0:1]
	s_mov_b32 s12, s86
	s_mov_b32 s24, s6
	s_mov_b64 s[28:29], s[22:23]
	s_mov_b64 s[26:27], s[8:9]
	global_store_dwordx4 v[18:19], v[2:5], off offset:256
	s_cbranch_vccz .LBB0_483
	s_waitcnt vmcnt(0)
	s_cmpk_gt_u32 s35, 0xff
	s_cbranch_scc1 .LBB0_494
	s_barrier

; #define PG8_STAGE(bufoff, gbase, voff) do { _Pragma("unroll") for (int _i = 0; _i < 2; ++_i) \
;         __builtin_amdgcn_global_load_lds((const unsigned*)((const char*)(gbase) + (voff)[_i]), (LAS unsigned*)(lds + (bufoff) + ldsw + _i * 8192), 16, 0, 0); } while (0)
; #define PG8_LDA(dst, b, h) do { _Pragma("unroll") for (int m = 0; m < 4; ++m) _Pragma("unroll") for (int k = 0; k < 2; ++k) dst[m][k] = *(const LAS bf16x8*)(lds + PG8_SA(b, h) + aoff + m * 2048 + k * 1024); } while (0)
; #define PG8_LDB(dst, b, h) do { _Pragma("unroll") for (int n = 0; n < 2; ++n) _Pragma("unroll") for (int k = 0; k < 2; ++k) dst[n][k] = *(const LAS bf16x8*)(lds + PG8_SB(b, h) + boff + n * 2048 + k * 1024); } while (0)
; #define PG8_MMA(ai, bj, At, Bt) do { __builtin_amdgcn_s_setprio(1); _Pragma("unroll") for (int m = 0; m < 4; ++m) _Pragma("unroll") for (int n = 0; n < 2; ++n) _Pragma("unroll") for (int k = 0; k < 2; ++k) \
;         acc[ai][bj][m][n] = __builtin_amdgcn_mfma_f32_16x16x32_bf16(Bt[n][k], At[m][k], acc[ai][bj][m][n], 0, 0, 0); __builtin_amdgcn_s_setprio(0); } while (0)
; #define PG8_WAIT_L(n) asm volatile("s_waitcnt lgkmcnt(" #n ")" ::: "memory")
; template <class Epi>
; DI void gemm_phase(int wv, LAS unsigned char* lds, const GemmD g, const Epi& E) {
;     ...
;         const bool has_next = S.next(ui + 1, nxt);
;         const char* nA = has_next ? (const char*)g.A + (size_t)nxt.pm * 256 * g.lda * 2 : cA; const char* nB = has_next ? (const char*)g.Bt + PG8_BROW(nxt.pn) * (size_t)g.ldb * 2 : cB;
;         for (int t = 0; t < nt; t += 2) {
;             const bool last = (t == nt - 2);
;             const char* a1 = cA + (size_t)(t + 1) * kstep;
;             const char* a2 = last ? nA : cA + (size_t)(t + 2) * kstep; const char* b2 = last ? nB : cB + (size_t)(t + 2) * kstep;
;             const char* a3 = a2 + kstep; const char* b3 = b2 + kstep;
;             PG8_LDB(B0, 0, 0); PG8_SCHED; PG8_LDA(At, 0, 0); PG8_STAGE(PG8_SA(1, 1), a1 + hstepA, voffA);
;             PG8_WAIT_L(8); PG8_BAR; PG8_WAIT_L(0); PG8_MMA(0, 0, At, B0); PG8_BAR; PG8_SCHED;
;             PG8_LDB(B1, 0, 1); PG8_STAGE(PG8_SB(0, 0), b2, voffB);
;             PG8_BAR; PG8_WAIT_L(0); PG8_MMA(0, 1, At, B1); PG8_BAR;
;             PG8_LDA(At, 0, 1); PG8_STAGE(PG8_SA(0, 0), a2, voffA);
;             PG8_BAR; PG8_WAIT_L(0); PG8_MMA(1, 0, At, B0); PG8_BAR; PG8_SCHED;
.LBB0_543:
	s_ashr_i32 s23, s22, 31
	s_lshl_b64 s[18:19], s[22:23], s85
	v_cmp_lt_i64_e32 vcc, s[24:25], v[174:175]
	s_add_u32 s24, s81, s18
	s_addc_u32 s25, s80, s19
	s_and_b64 s[18:19], vcc, exec
	s_cselect_b32 s23, s25, s29
	s_cselect_b32 s68, s24, s28
	s_lshl_b32 s18, s55, 8
	s_ashr_i32 s19, s18, 31
	s_lshl_b64 s[18:19], s[18:19], s9
	s_add_u32 s26, s82, s18
	s_addc_u32 s27, s83, s19
	s_and_b64 s[18:19], vcc, exec
	s_cselect_b32 vcc_lo, s27, s31
	s_cselect_b32 vcc_hi, s26, s30
	s_add_u32 s28, s28, 0x80
	s_addc_u32 s29, s29, 0
	s_add_u32 s37, s30, 0x100
	s_addc_u32 s18, s31, 0
	s_mov_b32 s19, 0
	s_add_i32 s95, s19, 2
	s_add_u32 s2, s28, 0x80
	s_addc_u32 s3, s29, 0
	s_add_i32 s94, 0, 0x10000
	v_add_u32_e32 v145, s94, v141
	ds_read_b128 v[146:149], v145
	ds_read_b128 v[150:153], v145 offset:1024
	ds_read_b128 v[154:157], v145 offset:2048
	ds_read_b128 v[158:161], v145 offset:3072
	s_cmp_eq_u32 s17, s19
	s_cselect_b32 s31, s23, s3
	s_cselect_b32 s30, s68, s2
	s_cselect_b32 s35, vcc_lo, s18
	s_cselect_b32 s34, vcc_hi, s37
	v_lshl_add_u64 v[200:201], s[28:29], 0, v[136:137]
	s_add_i32 m0, s86, 0xc000
	ds_read_b128 v[162:165], v144
	ds_read_b128 v[168:171], v144 offset:1024
	ds_read_b128 v[176:179], v144 offset:2048
	ds_read_b128 v[180:183], v144 offset:3072
	ds_read_b128 v[184:187], v144 offset:4096
	ds_read_b128 v[188:191], v144 offset:5120
	ds_read_b128 v[192:195], v144 offset:6144
	ds_read_b128 v[196:199], v144 offset:7168
	global_load_lds_dwordx4 v[200:201], off
	v_lshl_add_u64 v[200:201], s[28:29], 0, v[138:139]
	s_add_i32 m0, s86, 0xe000
	s_nop 0
	global_load_lds_dwordx4 v[200:201], off
	s_waitcnt lgkmcnt(8)
	s_barrier
	s_waitcnt lgkmcnt(0)
	s_setprio 1
	s_waitcnt lgkmcnt(0)
	v_mfma_f32_16x16x32_bf16 v[126:129], v[146:149], v[162:165], 0
	v_mfma_f32_16x16x32_bf16 v[122:125], v[154:157], v[162:165], 0
	v_mfma_f32_16x16x32_bf16 v[118:121], v[146:149], v[176:179], 0
	v_mfma_f32_16x16x32_bf16 v[114:117], v[154:157], v[176:179], 0
	v_mfma_f32_16x16x32_bf16 v[102:105], v[146:149], v[184:187], 0
	v_mfma_f32_16x16x32_bf16 v[98:101], v[154:157], v[184:187], 0
	v_mfma_f32_16x16x32_bf16 v[86:89], v[146:149], v[192:195], 0
	v_mfma_f32_16x16x32_bf16 v[82:85], v[154:157], v[192:195], 0
	v_mfma_f32_16x16x32_bf16 v[126:129], v[150:153], v[168:171], v[126:129]
	v_mfma_f32_16x16x32_bf16 v[122:125], v[158:161], v[168:171], v[122:125]
	v_mfma_f32_16x16x32_bf16 v[118:121], v[150:153], v[180:183], v[118:121]
	v_mfma_f32_16x16x32_bf16 v[114:117], v[158:161], v[180:183], v[114:117]
	v_mfma_f32_16x16x32_bf16 v[102:105], v[150:153], v[188:191], v[102:105]
	v_mfma_f32_16x16x32_bf16 v[98:101], v[158:161], v[188:191], v[98:101]
	v_mfma_f32_16x16x32_bf16 v[86:89], v[150:153], v[196:199], v[86:89]
	v_mfma_f32_16x16x32_bf16 v[82:85], v[158:161], v[196:199], v[82:85]
	s_setprio 0
	s_barrier
	s_add_i32 s2, 0, 0x14000
	s_add_i32 s3, s94, s84
	v_add_u32_e32 v145, s2, v141
	v_lshl_add_u64 v[216:217], s[34:35], 0, v[0:1]
	s_mov_b32 m0, s3
	ds_read_b128 v[200:203], v145
	ds_read_b128 v[204:207], v145 offset:1024
	ds_read_b128 v[208:211], v145 offset:2048
	ds_read_b128 v[212:215], v145 offset:3072
	global_load_lds_dwordx4 v[216:217], off
	v_lshl_add_u64 v[218:219], s[34:35], 0, v[134:135]
	s_add_i32 m0, s3, 0x2000
	s_nop 0
	global_load_lds_dwordx4 v[218:219], off
	s_barrier
	s_waitcnt lgkmcnt(0)
	s_setprio 1
	s_waitcnt lgkmcnt(0)
	v_mfma_f32_16x16x32_bf16 v[110:113], v[200:203], v[162:165], 0
	v_mfma_f32_16x16x32_bf16 v[106:109], v[208:211], v[162:165], 0
	v_mfma_f32_16x16x32_bf16 v[94:97], v[200:203], v[176:179], 0
	v_mfma_f32_16x16x32_bf16 v[90:93], v[208:211], v[176:179], 0
	v_mfma_f32_16x16x32_bf16 v[78:81], v[200:203], v[184:187], 0
	v_mfma_f32_16x16x32_bf16 v[74:77], v[208:211], v[184:187], 0
	v_mfma_f32_16x16x32_bf16 v[70:73], v[200:203], v[192:195], 0
	v_mfma_f32_16x16x32_bf16 v[66:69], v[208:211], v[192:195], 0
	v_mfma_f32_16x16x32_bf16 v[110:113], v[204:207], v[168:171], v[110:113]
	v_mfma_f32_16x16x32_bf16 v[106:109], v[212:215], v[168:171], v[106:109]
	v_mfma_f32_16x16x32_bf16 v[94:97], v[204:207], v[180:183], v[94:97]
	v_mfma_f32_16x16x32_bf16 v[90:93], v[212:215], v[180:183], v[90:93]
	v_mfma_f32_16x16x32_bf16 v[78:81], v[204:207], v[188:191], v[78:81]
	v_mfma_f32_16x16x32_bf16 v[74:77], v[212:215], v[188:191], v[74:77]
	v_mfma_f32_16x16x32_bf16 v[70:73], v[204:207], v[196:199], v[70:73]
	v_mfma_f32_16x16x32_bf16 v[66:69], v[212:215], v[196:199], v[66:69]
	s_setprio 0
	s_mov_b32 m0, s86
	v_lshl_add_u64 v[220:221], s[30:31], 0, v[130:131]
	s_barrier
	ds_read_b128 v[162:165], v144 offset:16384
	ds_read_b128 v[168:171], v144 offset:17408
	ds_read_b128 v[176:179], v144 offset:18432
	ds_read_b128 v[180:183], v144 offset:19456
	ds_read_b128 v[184:187], v144 offset:20480
	ds_read_b128 v[188:191], v144 offset:21504
	ds_read_b128 v[192:195], v144 offset:22528
	ds_read_b128 v[196:199], v144 offset:23552
	global_load_lds_dwordx4 v[220:221], off
	v_lshl_add_u64 v[222:223], s[30:31], 0, v[132:133]
	s_mov_b32 m0, s87
	s_nop 0
	global_load_lds_dwordx4 v[222:223], off
	s_barrier
	s_waitcnt lgkmcnt(0)
	s_setprio 1
	s_waitcnt lgkmcnt(0)
	v_mfma_f32_16x16x32_bf16 v[62:65], v[146:149], v[162:165], 0
	v_mfma_f32_16x16x32_bf16 v[58:61], v[154:157], v[162:165], 0
	v_mfma_f32_16x16x32_bf16 v[54:57], v[146:149], v[176:179], 0
	v_mfma_f32_16x16x32_bf16 v[50:53], v[154:157], v[176:179], 0
	v_mfma_f32_16x16x32_bf16 v[38:41], v[146:149], v[184:187], 0
	v_mfma_f32_16x16x32_bf16 v[34:37], v[154:157], v[184:187], 0
	v_mfma_f32_16x16x32_bf16 v[22:25], v[146:149], v[192:195], 0
	v_mfma_f32_16x16x32_bf16 v[18:21], v[154:157], v[192:195], 0
	v_mfma_f32_16x16x32_bf16 v[62:65], v[150:153], v[168:171], v[62:65]
	v_mfma_f32_16x16x32_bf16 v[58:61], v[158:161], v[168:171], v[58:61]
	v_mfma_f32_16x16x32_bf16 v[54:57], v[150:153], v[180:183], v[54:57]
	v_mfma_f32_16x16x32_bf16 v[50:53], v[158:161], v[180:183], v[50:53]
	v_mfma_f32_16x16x32_bf16 v[38:41], v[150:153], v[188:191], v[38:41]
	v_mfma_f32_16x16x32_bf16 v[34:37], v[158:161], v[188:191], v[34:37]
	v_mfma_f32_16x16x32_bf16 v[22:25], v[150:153], v[196:199], v[22:25]
	v_mfma_f32_16x16x32_bf16 v[18:21], v[158:161], v[196:199], v[18:21]
	s_setprio 0
	s_barrier
; #define PG8_STAGE(bufoff, gbase, voff) do { _Pragma("unroll") for (int _i = 0; _i < 2; ++_i) \
;         __builtin_amdgcn_global_load_lds((const unsigned*)((const char*)(gbase) + (voff)[_i]), (LAS unsigned*)(lds + (bufoff) + ldsw + _i * 8192), 16, 0, 0); } while (0)
; #define PG8_LDA(dst, b, h) do { _Pragma("unroll") for (int m = 0; m < 4; ++m) _Pragma("unroll") for (int k = 0; k < 2; ++k) dst[m][k] = *(const LAS bf16x8*)(lds + PG8_SA(b, h) + aoff + m * 2048 + k * 1024); } while (0)
; #define PG8_LDB(dst, b, h) do { _Pragma("unroll") for (int n = 0; n < 2; ++n) _Pragma("unroll") for (int k = 0; k < 2; ++k) dst[n][k] = *(const LAS bf16x8*)(lds + PG8_SB(b, h) + boff + n * 2048 + k * 1024); } while (0)
; #define PG8_MMA(ai, bj, At, Bt) do { __builtin_amdgcn_s_setprio(1); _Pragma("unroll") for (int m = 0; m < 4; ++m) _Pragma("unroll") for (int n = 0; n < 2; ++n) _Pragma("unroll") for (int k = 0; k < 2; ++k) \
;         acc[ai][bj][m][n] = __builtin_amdgcn_mfma_f32_16x16x32_bf16(Bt[n][k], At[m][k], acc[ai][bj][m][n], 0, 0, 0); __builtin_amdgcn_s_setprio(0); } while (0)
; #define PG8_WAIT_V(n) asm volatile("s_waitcnt vmcnt(" #n ")" ::: "memory")
; #define PG8_WAIT_L(n) asm volatile("s_waitcnt lgkmcnt(" #n ")" ::: "memory")
; #define PG8_BAR __builtin_amdgcn_s_barrier()
; #define PG8_SCHED __builtin_amdgcn_sched_barrier(0)
; template <class Epi>
; DI void gemm_phase(int wv, LAS unsigned char* lds, const GemmD g, const Epi& E) {
;     ...
;             PG8_STAGE(PG8_SB(0, 1), b2 + hstepB, voffB);
;             PG8_WAIT_V(6); PG8_BAR; PG8_MMA(1, 1, At, B1); PG8_BAR;
;             PG8_LDB(B0, 1, 0); PG8_SCHED; PG8_LDA(At, 1, 0); PG8_STAGE(PG8_SA(0, 1), a2 + hstepA, voffA);
;             PG8_WAIT_L(8); PG8_BAR; PG8_WAIT_L(0); PG8_MMA(0, 0, At, B0); PG8_BAR; PG8_SCHED;
;             PG8_LDB(B1, 1, 1); PG8_STAGE(PG8_SB(1, 0), b3, voffB);
	s_add_u32 s34, s34, s56
	s_addc_u32 s35, s35, 0
	s_add_i32 s2, s2, s84
	v_lshl_add_u64 v[224:225], s[34:35], 0, v[0:1]
	s_mov_b32 m0, s2
	v_lshl_add_u64 v[226:227], s[34:35], 0, v[134:135]
	global_load_lds_dwordx4 v[224:225], off
	s_add_i32 m0, s2, 0x2000
	s_nop 0
	global_load_lds_dwordx4 v[226:227], off
	s_waitcnt vmcnt(6)
	s_barrier
	s_setprio 1
	v_mfma_f32_16x16x32_bf16 v[46:49], v[200:203], v[162:165], 0
	v_mfma_f32_16x16x32_bf16 v[42:45], v[208:211], v[162:165], 0
	v_mfma_f32_16x16x32_bf16 v[30:33], v[200:203], v[176:179], 0
	v_mfma_f32_16x16x32_bf16 v[26:29], v[208:211], v[176:179], 0
	v_mfma_f32_16x16x32_bf16 v[14:17], v[200:203], v[184:187], 0
	v_mfma_f32_16x16x32_bf16 v[10:13], v[208:211], v[184:187], 0
	v_mfma_f32_16x16x32_bf16 v[6:9], v[200:203], v[192:195], 0
	v_mfma_f32_16x16x32_bf16 v[2:5], v[208:211], v[192:195], 0
	v_mfma_f32_16x16x32_bf16 v[46:49], v[204:207], v[168:171], v[46:49]
	v_mfma_f32_16x16x32_bf16 v[42:45], v[212:215], v[168:171], v[42:45]
	v_mfma_f32_16x16x32_bf16 v[30:33], v[204:207], v[180:183], v[30:33]
	v_mfma_f32_16x16x32_bf16 v[26:29], v[212:215], v[180:183], v[26:29]
	v_mfma_f32_16x16x32_bf16 v[14:17], v[204:207], v[188:191], v[14:17]
	v_mfma_f32_16x16x32_bf16 v[10:13], v[212:215], v[188:191], v[10:13]
	v_mfma_f32_16x16x32_bf16 v[6:9], v[204:207], v[196:199], v[6:9]
	v_mfma_f32_16x16x32_bf16 v[2:5], v[212:215], v[196:199], v[2:5]
	s_setprio 0
	s_add_i32 s2, 0, 0x18000
	v_add_u32_e32 v145, s2, v141
	s_barrier
	ds_read_b128 v[146:149], v145
	ds_read_b128 v[150:153], v145 offset:1024
	ds_read_b128 v[154:157], v145 offset:2048
	ds_read_b128 v[158:161], v145 offset:3072
	s_add_u32 s30, s30, s56
	s_addc_u32 s31, s31, 0
	s_mov_b32 m0, s74
	v_lshl_add_u64 v[200:201], s[30:31], 0, v[130:131]
	ds_read_b128 v[162:165], v144 offset:32768
	ds_read_b128 v[168:171], v144 offset:33792
	ds_read_b128 v[176:179], v144 offset:34816
	ds_read_b128 v[180:183], v144 offset:35840
	ds_read_b128 v[184:187], v144 offset:36864
	ds_read_b128 v[188:191], v144 offset:37888
	ds_read_b128 v[192:195], v144 offset:38912
	ds_read_b128 v[196:199], v144 offset:39936
	global_load_lds_dwordx4 v[200:201], off
	v_lshl_add_u64 v[200:201], s[30:31], 0, v[132:133]
	s_mov_b32 m0, s41
	s_nop 0
	global_load_lds_dwordx4 v[200:201], off
	s_waitcnt lgkmcnt(8)
	s_barrier
	s_waitcnt lgkmcnt(0)
	s_setprio 1
	s_waitcnt lgkmcnt(0)
	v_mfma_f32_16x16x32_bf16 v[126:129], v[146:149], v[162:165], v[126:129]
	v_mfma_f32_16x16x32_bf16 v[122:125], v[154:157], v[162:165], v[122:125]
	v_mfma_f32_16x16x32_bf16 v[118:121], v[146:149], v[176:179], v[118:121]
	v_mfma_f32_16x16x32_bf16 v[114:117], v[154:157], v[176:179], v[114:117]
	v_mfma_f32_16x16x32_bf16 v[102:105], v[146:149], v[184:187], v[102:105]
	v_mfma_f32_16x16x32_bf16 v[98:101], v[154:157], v[184:187], v[98:101]
	v_mfma_f32_16x16x32_bf16 v[86:89], v[146:149], v[192:195], v[86:89]
	v_mfma_f32_16x16x32_bf16 v[82:85], v[154:157], v[192:195], v[82:85]
	v_mfma_f32_16x16x32_bf16 v[126:129], v[150:153], v[168:171], v[126:129]
	v_mfma_f32_16x16x32_bf16 v[122:125], v[158:161], v[168:171], v[122:125]
	v_mfma_f32_16x16x32_bf16 v[118:121], v[150:153], v[180:183], v[118:121]
	v_mfma_f32_16x16x32_bf16 v[114:117], v[158:161], v[180:183], v[114:117]
	v_mfma_f32_16x16x32_bf16 v[102:105], v[150:153], v[188:191], v[102:105]
	v_mfma_f32_16x16x32_bf16 v[98:101], v[158:161], v[188:191], v[98:101]
	v_mfma_f32_16x16x32_bf16 v[86:89], v[150:153], v[196:199], v[86:89]
	v_mfma_f32_16x16x32_bf16 v[82:85], v[158:161], v[196:199], v[82:85]
	s_setprio 0
	s_barrier
	s_add_i32 s3, 0, 0x1c000
	s_add_i32 s2, s2, s84
	v_add_u32_e32 v145, s3, v141
	v_lshl_add_u64 v[216:217], v[216:217], 0, s[58:59]
	s_mov_b32 m0, s2
	ds_read_b128 v[200:203], v145
	ds_read_b128 v[204:207], v145 offset:1024
	ds_read_b128 v[208:211], v145 offset:2048
	ds_read_b128 v[212:215], v145 offset:3072
	global_load_lds_dwordx4 v[216:217], off
	v_lshl_add_u64 v[216:217], v[218:219], 0, s[58:59]
	s_add_i32 m0, s2, 0x2000
	s_nop 0
	global_load_lds_dwordx4 v[216:217], off
	s_barrier
; #define PG8_STAGE(bufoff, gbase, voff) do { _Pragma("unroll") for (int _i = 0; _i < 2; ++_i) \
;         __builtin_amdgcn_global_load_lds((const unsigned*)((const char*)(gbase) + (voff)[_i]), (LAS unsigned*)(lds + (bufoff) + ldsw + _i * 8192), 16, 0, 0); } while (0)
; #define PG8_LDA(dst, b, h) do { _Pragma("unroll") for (int m = 0; m < 4; ++m) _Pragma("unroll") for (int k = 0; k < 2; ++k) dst[m][k] = *(const LAS bf16x8*)(lds + PG8_SA(b, h) + aoff + m * 2048 + k * 1024); } while (0)
; #define PG8_MMA(ai, bj, At, Bt) do { __builtin_amdgcn_s_setprio(1); _Pragma("unroll") for (int m = 0; m < 4; ++m) _Pragma("unroll") for (int n = 0; n < 2; ++n) _Pragma("unroll") for (int k = 0; k < 2; ++k) \
;         acc[ai][bj][m][n] = __builtin_amdgcn_mfma_f32_16x16x32_bf16(Bt[n][k], At[m][k], acc[ai][bj][m][n], 0, 0, 0); __builtin_amdgcn_s_setprio(0); } while (0)
; #define PG8_WAIT_V(n) asm volatile("s_waitcnt vmcnt(" #n ")" ::: "memory")
; #define PG8_WAIT_L(n) asm volatile("s_waitcnt lgkmcnt(" #n ")" ::: "memory")
; #define PG8_BAR __builtin_amdgcn_s_barrier()
; #define PG8_SCHED __builtin_amdgcn_sched_barrier(0)
; template <class Epi>
; DI void gemm_phase(int wv, LAS unsigned char* lds, const GemmD g, const Epi& E) {
;     ...
;             PG8_BAR; PG8_WAIT_L(0); PG8_MMA(0, 1, At, B1); PG8_BAR;
;             PG8_LDA(At, 1, 1); PG8_STAGE(PG8_SA(1, 0), a3, voffA);
;             PG8_BAR; PG8_WAIT_L(0); PG8_MMA(1, 0, At, B0); PG8_BAR; PG8_SCHED;
;             PG8_STAGE(PG8_SB(1, 1), b3 + hstepB, voffB);
;             PG8_WAIT_V(6); PG8_BAR; PG8_MMA(1, 1, At, B1); PG8_BAR;
;         }
	s_waitcnt lgkmcnt(0)
	s_setprio 1
	s_waitcnt lgkmcnt(0)
	v_mfma_f32_16x16x32_bf16 v[110:113], v[200:203], v[162:165], v[110:113]
	v_mfma_f32_16x16x32_bf16 v[106:109], v[208:211], v[162:165], v[106:109]
	v_mfma_f32_16x16x32_bf16 v[94:97], v[200:203], v[176:179], v[94:97]
	v_mfma_f32_16x16x32_bf16 v[90:93], v[208:211], v[176:179], v[90:93]
	v_mfma_f32_16x16x32_bf16 v[78:81], v[200:203], v[184:187], v[78:81]
	v_mfma_f32_16x16x32_bf16 v[74:77], v[208:211], v[184:187], v[74:77]
	v_mfma_f32_16x16x32_bf16 v[70:73], v[200:203], v[192:195], v[70:73]
	v_mfma_f32_16x16x32_bf16 v[66:69], v[208:211], v[192:195], v[66:69]
	v_mfma_f32_16x16x32_bf16 v[110:113], v[204:207], v[168:171], v[110:113]
	v_mfma_f32_16x16x32_bf16 v[106:109], v[212:215], v[168:171], v[106:109]
	v_mfma_f32_16x16x32_bf16 v[94:97], v[204:207], v[180:183], v[94:97]
	v_mfma_f32_16x16x32_bf16 v[90:93], v[212:215], v[180:183], v[90:93]
	v_mfma_f32_16x16x32_bf16 v[78:81], v[204:207], v[188:191], v[78:81]
	v_mfma_f32_16x16x32_bf16 v[74:77], v[212:215], v[188:191], v[74:77]
	v_mfma_f32_16x16x32_bf16 v[70:73], v[204:207], v[196:199], v[70:73]
	v_mfma_f32_16x16x32_bf16 v[66:69], v[212:215], v[196:199], v[66:69]
	s_setprio 0
	s_mov_b32 m0, s13
	v_lshl_add_u64 v[216:217], v[220:221], 0, s[58:59]
	s_barrier
	ds_read_b128 v[162:165], v144 offset:49152
	ds_read_b128 v[168:171], v144 offset:50176
	ds_read_b128 v[176:179], v144 offset:51200
	ds_read_b128 v[180:183], v144 offset:52224
	ds_read_b128 v[184:187], v144 offset:53248
	ds_read_b128 v[188:191], v144 offset:54272
	ds_read_b128 v[192:195], v144 offset:55296
	ds_read_b128 v[196:199], v144 offset:56320
	global_load_lds_dwordx4 v[216:217], off
	v_lshl_add_u64 v[216:217], v[222:223], 0, s[58:59]
	s_mov_b32 m0, s16
	s_nop 0
	global_load_lds_dwordx4 v[216:217], off
	s_barrier
	s_waitcnt lgkmcnt(0)
	s_setprio 1
	s_waitcnt lgkmcnt(0)
	v_mfma_f32_16x16x32_bf16 v[62:65], v[146:149], v[162:165], v[62:65]
	v_mfma_f32_16x16x32_bf16 v[58:61], v[154:157], v[162:165], v[58:61]
	v_mfma_f32_16x16x32_bf16 v[54:57], v[146:149], v[176:179], v[54:57]
	v_mfma_f32_16x16x32_bf16 v[50:53], v[154:157], v[176:179], v[50:53]
	v_mfma_f32_16x16x32_bf16 v[38:41], v[146:149], v[184:187], v[38:41]
	v_mfma_f32_16x16x32_bf16 v[34:37], v[154:157], v[184:187], v[34:37]
	v_mfma_f32_16x16x32_bf16 v[22:25], v[146:149], v[192:195], v[22:25]
	v_mfma_f32_16x16x32_bf16 v[18:21], v[154:157], v[192:195], v[18:21]
	v_mfma_f32_16x16x32_bf16 v[62:65], v[150:153], v[168:171], v[62:65]
	v_mfma_f32_16x16x32_bf16 v[58:61], v[158:161], v[168:171], v[58:61]
	v_mfma_f32_16x16x32_bf16 v[54:57], v[150:153], v[180:183], v[54:57]
	v_mfma_f32_16x16x32_bf16 v[50:53], v[158:161], v[180:183], v[50:53]
	v_mfma_f32_16x16x32_bf16 v[38:41], v[150:153], v[188:191], v[38:41]
	v_mfma_f32_16x16x32_bf16 v[34:37], v[158:161], v[188:191], v[34:37]
	v_mfma_f32_16x16x32_bf16 v[22:25], v[150:153], v[196:199], v[22:25]
	v_mfma_f32_16x16x32_bf16 v[18:21], v[158:161], v[196:199], v[18:21]
	s_setprio 0
	s_barrier
	s_add_i32 s2, s3, s84
	v_lshl_add_u64 v[146:147], v[224:225], 0, s[58:59]
	s_mov_b32 m0, s2
	s_nop 0
	global_load_lds_dwordx4 v[146:147], off
	v_lshl_add_u64 v[146:147], v[226:227], 0, s[58:59]
	s_add_i32 m0, s2, 0x2000
	s_nop 0
	global_load_lds_dwordx4 v[146:147], off
	s_waitcnt vmcnt(6)
	s_barrier
	s_setprio 1
	v_mfma_f32_16x16x32_bf16 v[46:49], v[200:203], v[162:165], v[46:49]
	v_mfma_f32_16x16x32_bf16 v[42:45], v[208:211], v[162:165], v[42:45]
	v_mfma_f32_16x16x32_bf16 v[30:33], v[200:203], v[176:179], v[30:33]
	v_mfma_f32_16x16x32_bf16 v[26:29], v[208:211], v[176:179], v[26:29]
	v_mfma_f32_16x16x32_bf16 v[14:17], v[200:203], v[184:187], v[14:17]
	v_mfma_f32_16x16x32_bf16 v[10:13], v[208:211], v[184:187], v[10:13]
	v_mfma_f32_16x16x32_bf16 v[6:9], v[200:203], v[192:195], v[6:9]
	v_mfma_f32_16x16x32_bf16 v[2:5], v[208:211], v[192:195], v[2:5]
	v_mfma_f32_16x16x32_bf16 v[46:49], v[204:207], v[168:171], v[46:49]
	v_mfma_f32_16x16x32_bf16 v[42:45], v[212:215], v[168:171], v[42:45]
	v_mfma_f32_16x16x32_bf16 v[30:33], v[204:207], v[180:183], v[30:33]
	v_mfma_f32_16x16x32_bf16 v[26:29], v[212:215], v[180:183], v[26:29]
	v_mfma_f32_16x16x32_bf16 v[14:17], v[204:207], v[188:191], v[14:17]
	v_mfma_f32_16x16x32_bf16 v[10:13], v[212:215], v[188:191], v[10:13]
	v_mfma_f32_16x16x32_bf16 v[6:9], v[204:207], v[196:199], v[6:9]
	v_mfma_f32_16x16x32_bf16 v[2:5], v[212:215], v[196:199], v[2:5]
	s_setprio 0
	s_add_u32 s28, s28, 0x100
	s_addc_u32 s29, s29, 0
	s_add_u32 s37, s37, 0x100
	s_addc_u32 s18, s18, 0
	s_cmp_ge_u32 s95, s38
	s_mov_b32 s19, s95
	s_barrier
	s_cbranch_scc0 .LBB0_544
	s_branch .Lgemm_epi_c

; DI unsigned pk2(float lo, float hi) { f32x2 f = {lo, hi}; bf2_t v = __builtin_convertvector(f, bf2_t); return __builtin_bit_cast(unsigned, v); }
; #define PG8_WAIT_V(n) asm volatile("s_waitcnt vmcnt(" #n ")" ::: "memory")
; #define PG8_BAR __builtin_amdgcn_s_barrier()
;     DI void operator()(const f32x4 (&acc)[2][2][4][2], const Unit& u, int wr, int wc, int fr, int fq) const {
;     ...
;             for (int m = 0; m < 4; ++m) { bf16_t* rowp = O + (size_t)(row0 + ai * HALF + m * 16) * ldc + col0;
; #pragma unroll
;                 for (int bj = 0; bj < 2; ++bj) { f32x4 v0 = acc[ai][bj][m][0], v1 = acc[ai][bj][m][1];
;                     if (ACT == 1) {
; #pragma unroll
;                         for (int j = 0; j < 4; ++j) { float a = fmaxf(v0[j], 0.f), b = fmaxf(v1[j], 0.f); v0[j] = a * a; v1[j] = b * b; } }
;                     u32x4 w; w.x = pk2(v0[0], v0[1]); w.y = pk2(v0[2], v0[3]); w.z = pk2(v1[0], v1[1]); w.w = pk2(v1[2], v1[3]);
;                     *(u32x4*)(rowp + bj * HALF) = w; } }
; template <class Epi>
; DI void gemm_phase(int wv, LAS unsigned char* lds, const GemmD g, const Epi& E) {
;     ...
;         E(acc, cur, wr, wc, fr, fq);
;         if (!has_next) break;
; #pragma unroll
;         for (int a = 0; a < 2; ++a)
; #pragma unroll
;             for (int b = 0; b < 2; ++b)
; #pragma unroll
;                 for (int m = 0; m < 4; ++m)
; #pragma unroll
;                     for (int n = 0; n < 2; ++n) acc[a][b][m][n] = (f32x4){0.f, 0.f, 0.f, 0.f};
;         cur = nxt; cA = nA; cB = nB; ++ui;
;     }
;     PG8_WAIT_V(0);
;     if (wr == 0) PG8_BAR;
;     PG8_BAR;
.Lgemm_epi_c:
	v_lshl_add_u32 v146, s8, 8, v140
	v_lshl_or_b32 v148, s12, 8, v143
	v_ashrrev_i32_e32 v147, 31, v146
	v_ashrrev_i32_e32 v149, 31, v148
	v_lshlrev_b64 v[150:151], 11, v[146:147]
	v_lshl_add_u64 v[150:151], s[6:7], 0, v[150:151]
	v_lshlrev_b64 v[148:149], 1, v[148:149]
	v_lshl_add_u64 v[150:151], v[150:151], 0, v[148:149]
	s_mov_b32 s94, 0x40000
	s_mov_b64 s[18:19], 0x40000
	v_cvt_pk_bf16_f32 v62, v62, v63
	v_cvt_pk_bf16_f32 v63, v64, v65
	v_cvt_pk_bf16_f32 v64, v58, v59
	v_add_co_u32_e32 v58, vcc, s94, v150
	v_cvt_pk_bf16_f32 v70, v70, v71
	v_cvt_pk_bf16_f32 v71, v72, v73
	v_cvt_pk_bf16_f32 v72, v66, v67
	v_lshl_add_u64 v[66:67], v[150:151], 0, s[18:19]
	v_addc_co_u32_e32 v59, vcc, 0, v151, vcc
	v_cvt_pk_bf16_f32 v46, v46, v47
	v_cvt_pk_bf16_f32 v47, v48, v49
	v_cvt_pk_bf16_f32 v48, v42, v43
	v_cvt_pk_bf16_f32 v49, v44, v45
	s_mov_b32 s2, 0x48000
	v_cvt_pk_bf16_f32 v110, v110, v111
	v_cvt_pk_bf16_f32 v111, v112, v113
	v_cvt_pk_bf16_f32 v112, v106, v107
	v_or_b32_e32 v106, 16, v146
	global_store_dwordx4 v[66:67], v[46:49], off offset:256
	s_mov_b64 s[18:19], 0x48000
	v_ashrrev_i32_e32 v107, 31, v106
	v_add_co_u32_e32 v48, vcc, s2, v150
	v_cvt_pk_bf16_f32 v94, v94, v95
	v_cvt_pk_bf16_f32 v95, v96, v97
	v_cvt_pk_bf16_f32 v96, v90, v91
	v_or_b32_e32 v90, 32, v146
	v_lshl_add_u64 v[46:47], v[150:151], 0, s[18:19]
	v_addc_co_u32_e32 v49, vcc, 0, v151, vcc
	v_cvt_pk_bf16_f32 v30, v30, v31
	v_cvt_pk_bf16_f32 v31, v32, v33
	v_cvt_pk_bf16_f32 v32, v26, v27
	v_cvt_pk_bf16_f32 v33, v28, v29
	s_mov_b32 s2, 0x50000
	v_lshlrev_b64 v[106:107], 11, v[106:107]
	v_ashrrev_i32_e32 v91, 31, v90
	v_cvt_pk_bf16_f32 v78, v78, v79
	v_cvt_pk_bf16_f32 v79, v80, v81
	v_cvt_pk_bf16_f32 v80, v74, v75
	v_or_b32_e32 v74, 48, v146
	global_store_dwordx4 v[46:47], v[30:33], off offset:256
	s_mov_b64 s[18:19], 0x50000
	v_cvt_pk_bf16_f32 v113, v108, v109
	v_add_co_u32_e32 v32, vcc, s2, v150
	v_lshl_add_u64 v[106:107], s[6:7], 0, v[106:107]
	v_lshlrev_b64 v[90:91], 11, v[90:91]
	v_ashrrev_i32_e32 v75, 31, v74
	v_lshl_add_u64 v[30:31], v[150:151], 0, s[18:19]
	v_addc_co_u32_e32 v33, vcc, 0, v151, vcc
	v_cvt_pk_bf16_f32 v14, v14, v15
	v_cvt_pk_bf16_f32 v15, v16, v17
	v_cvt_pk_bf16_f32 v16, v10, v11
	v_cvt_pk_bf16_f32 v17, v12, v13
	s_mov_b32 s2, 0x58000
	global_store_dwordx4 v[150:151], v[110:113], off offset:256
	v_cvt_pk_bf16_f32 v97, v92, v93
	v_lshl_add_u64 v[90:91], s[6:7], 0, v[90:91]
	v_lshl_add_u64 v[110:111], v[106:107], 0, v[148:149]
	v_lshlrev_b64 v[74:75], 11, v[74:75]
	global_store_dwordx4 v[30:31], v[14:17], off offset:256
	global_store_dwordx4 v[110:111], v[94:97], off offset:256
	v_cvt_pk_bf16_f32 v81, v76, v77
	v_add_co_u32_e32 v16, vcc, s2, v150
	v_lshl_add_u64 v[94:95], v[90:91], 0, v[148:149]
	v_lshl_add_u64 v[74:75], s[6:7], 0, v[74:75]
	s_mov_b64 s[18:19], 0x58000
	v_addc_co_u32_e32 v17, vcc, 0, v151, vcc
	v_cvt_pk_bf16_f32 v126, v126, v127
	v_cvt_pk_bf16_f32 v127, v128, v129
	v_cvt_pk_bf16_f32 v128, v122, v123
	v_cvt_pk_bf16_f32 v129, v124, v125
	v_cvt_pk_bf16_f32 v106, v118, v119
	v_cvt_pk_bf16_f32 v107, v120, v121
	v_cvt_pk_bf16_f32 v108, v114, v115
	v_cvt_pk_bf16_f32 v109, v116, v117
	v_cvt_pk_bf16_f32 v90, v102, v103
	v_cvt_pk_bf16_f32 v91, v104, v105
	v_cvt_pk_bf16_f32 v92, v98, v99
	v_cvt_pk_bf16_f32 v93, v100, v101
	global_store_dwordx4 v[94:95], v[78:81], off offset:256
	v_cvt_pk_bf16_f32 v76, v82, v83
	v_cvt_pk_bf16_f32 v77, v84, v85
	v_lshl_add_u64 v[78:79], v[74:75], 0, v[148:149]
	v_cvt_pk_bf16_f32 v74, v86, v87
	v_cvt_pk_bf16_f32 v75, v88, v89
	v_cvt_pk_bf16_f32 v73, v68, v69
	v_cvt_pk_bf16_f32 v65, v60, v61
	v_cvt_pk_bf16_f32 v42, v54, v55
	v_cvt_pk_bf16_f32 v43, v56, v57
	v_cvt_pk_bf16_f32 v44, v50, v51
	v_cvt_pk_bf16_f32 v45, v52, v53
	v_cvt_pk_bf16_f32 v26, v38, v39
	v_cvt_pk_bf16_f32 v27, v40, v41
	v_cvt_pk_bf16_f32 v28, v34, v35
	v_cvt_pk_bf16_f32 v29, v36, v37
	v_lshl_add_u64 v[14:15], v[150:151], 0, s[18:19]
	v_cvt_pk_bf16_f32 v10, v22, v23
	v_cvt_pk_bf16_f32 v11, v24, v25
	v_cvt_pk_bf16_f32 v12, v18, v19
	v_cvt_pk_bf16_f32 v13, v20, v21
	v_cvt_pk_bf16_f32 v6, v6, v7
	v_cvt_pk_bf16_f32 v7, v8, v9
	v_cvt_pk_bf16_f32 v8, v2, v3
	v_cvt_pk_bf16_f32 v9, v4, v5
	s_and_b64 vcc, exec, s[0:1]
	s_mov_b32 s12, s55
	s_mov_b32 s8, s22
	s_mov_b64 s[30:31], s[26:27]
	s_mov_b64 s[28:29], s[24:25]
	global_store_dwordx4 v[150:151], v[126:129], off
	global_store_dwordx4 v[110:111], v[106:109], off
	global_store_dwordx4 v[94:95], v[90:93], off
	global_store_dwordx4 v[78:79], v[74:77], off
	global_store_dwordx4 v[78:79], v[70:73], off offset:256
	global_store_dwordx4 v[58:59], v[62:65], off
	global_store_dwordx4 v[48:49], v[42:45], off
	global_store_dwordx4 v[32:33], v[26:29], off
	global_store_dwordx4 v[16:17], v[10:13], off
	global_store_dwordx4 v[14:15], v[6:9], off offset:256
	s_cbranch_vccz .LBB0_537
	s_waitcnt vmcnt(0)
	s_cmpk_gt_u32 s78, 0xff
	s_cbranch_scc1 .LBB0_548
	s_barrier
